# GEMM loops: LDS-DMA loads use SGPR base plus 32-bit VGPR offset form, 56 64-bit VALU address adds removed
# speedup vs baseline: 1.0524x; 1.0023x over previous
.LBB0_253:
	s_ashr_i32 s31, s30, 31
	v_cmp_lt_i64_e32 vcc, s[28:29], v[134:135]
	s_lshl_b64 s[28:29], s[30:31], 19
	v_readlane_b32 s36, v253, 45
	v_readlane_b32 s37, v253, 46
	s_add_u32 s36, s36, s28
	s_addc_u32 s37, s37, s29
	s_and_b64 s[28:29], vcc, exec
	s_cselect_b32 s31, s37, s21
	s_cselect_b32 s65, s36, s20
	s_ashr_i32 s1, s0, 31
	s_lshl_b64 s[28:29], s[0:1], 19
	v_readlane_b32 s42, v255, 0
	v_readlane_b32 s43, v255, 1
	s_add_u32 s42, s42, s28
	s_addc_u32 s43, s43, s29
	s_and_b64 s[28:29], vcc, exec
	s_cselect_b32 s1, s43, s3
	s_cselect_b32 s66, s42, s2
	s_add_u32 s20, s20, 0x40080
	s_addc_u32 s21, s21, 0
	s_add_u32 s67, s2, 0x100
	s_addc_u32 s68, s3, 0
	s_mov_b32 s69, -2
	s_waitcnt lgkmcnt(0)
	s_add_u32 s2, s20, 0xfffc0080
	s_addc_u32 s3, s21, -1
	s_add_i32 s70, 0, 0x10000
	v_add_u32_e32 v0, s70, v143
	ds_read_b128 v[156:159], v0
	ds_read_b128 v[170:173], v0 offset:1024
	ds_read_b128 v[174:177], v0 offset:2048
	ds_read_b128 v[178:181], v0 offset:3072
	s_cmp_eq_u32 s69, 12
	s_cselect_b32 s29, s31, s3
	s_cselect_b32 s28, s65, s2
	s_cselect_b32 s3, s1, s68
	s_cselect_b32 s2, s66, s67
	s_add_i32 m0, s33, 0xc000
	ds_read_b128 v[182:185], v169
	ds_read_b128 v[186:189], v169 offset:1024
	ds_read_b128 v[190:193], v169 offset:2048
	ds_read_b128 v[194:197], v169 offset:3072
	ds_read_b128 v[198:201], v169 offset:4096
	ds_read_b128 v[202:205], v169 offset:5120
	ds_read_b128 v[206:209], v169 offset:6144
	ds_read_b128 v[210:213], v169 offset:7168
	global_load_lds_dwordx4 v152, s[20:21]
	s_add_i32 m0, s33, 0xe000
	s_nop 0
	global_load_lds_dwordx4 v154, s[20:21]
	s_waitcnt lgkmcnt(8)
	s_barrier
	s_waitcnt lgkmcnt(0)
	v_mfma_f32_16x16x32_bf16 v[126:129], v[156:159], v[182:185], 0
	v_mfma_f32_16x16x32_bf16 v[122:125], v[174:177], v[182:185], 0
	v_mfma_f32_16x16x32_bf16 v[110:113], v[156:159], v[190:193], 0
	v_mfma_f32_16x16x32_bf16 v[106:109], v[174:177], v[190:193], 0
	v_mfma_f32_16x16x32_bf16 v[94:97], v[156:159], v[198:201], 0
	v_mfma_f32_16x16x32_bf16 v[90:93], v[174:177], v[198:201], 0
	v_mfma_f32_16x16x32_bf16 v[78:81], v[156:159], v[206:209], 0
	v_mfma_f32_16x16x32_bf16 v[74:77], v[174:177], v[206:209], 0
	v_mfma_f32_16x16x32_bf16 v[126:129], v[170:173], v[186:189], v[126:129]
	v_mfma_f32_16x16x32_bf16 v[122:125], v[178:181], v[186:189], v[122:125]
	v_mfma_f32_16x16x32_bf16 v[110:113], v[170:173], v[194:197], v[110:113]
	v_mfma_f32_16x16x32_bf16 v[106:109], v[178:181], v[194:197], v[106:109]
	v_mfma_f32_16x16x32_bf16 v[94:97], v[170:173], v[202:205], v[94:97]
	v_mfma_f32_16x16x32_bf16 v[90:93], v[178:181], v[202:205], v[90:93]
	v_mfma_f32_16x16x32_bf16 v[78:81], v[170:173], v[210:213], v[78:81]
	v_mfma_f32_16x16x32_bf16 v[74:77], v[178:181], v[210:213], v[74:77]
	s_barrier
	s_add_i32 s72, 0, 0x14000
	s_add_i32 s70, s70, s23
	v_add_u32_e32 v0, s72, v143
	s_mov_b32 m0, s70
	ds_read_b128 v[214:217], v0
	ds_read_b128 v[218:221], v0 offset:1024
	ds_read_b128 v[222:225], v0 offset:2048
	ds_read_b128 v[226:229], v0 offset:3072
	global_load_lds_dwordx4 v148, s[2:3]
	s_add_i32 m0, s70, 0x2000
	s_nop 0
	global_load_lds_dwordx4 v144, s[2:3]
	s_barrier
	s_waitcnt lgkmcnt(0)
	v_mfma_f32_16x16x32_bf16 v[118:121], v[214:217], v[182:185], 0
	v_mfma_f32_16x16x32_bf16 v[114:117], v[222:225], v[182:185], 0
	v_mfma_f32_16x16x32_bf16 v[102:105], v[214:217], v[190:193], 0
	v_mfma_f32_16x16x32_bf16 v[98:101], v[222:225], v[190:193], 0
	v_mfma_f32_16x16x32_bf16 v[86:89], v[214:217], v[198:201], 0
	v_mfma_f32_16x16x32_bf16 v[82:85], v[222:225], v[198:201], 0
	v_mfma_f32_16x16x32_bf16 v[70:73], v[214:217], v[206:209], 0
	v_mfma_f32_16x16x32_bf16 v[66:69], v[222:225], v[206:209], 0
	v_mfma_f32_16x16x32_bf16 v[118:121], v[218:221], v[186:189], v[118:121]
	v_mfma_f32_16x16x32_bf16 v[114:117], v[226:229], v[186:189], v[114:117]
	v_mfma_f32_16x16x32_bf16 v[102:105], v[218:221], v[194:197], v[102:105]
	v_mfma_f32_16x16x32_bf16 v[98:101], v[226:229], v[194:197], v[98:101]
	v_mfma_f32_16x16x32_bf16 v[86:89], v[218:221], v[202:205], v[86:89]
	v_mfma_f32_16x16x32_bf16 v[82:85], v[226:229], v[202:205], v[82:85]
	v_mfma_f32_16x16x32_bf16 v[70:73], v[218:221], v[210:213], v[70:73]
	v_mfma_f32_16x16x32_bf16 v[66:69], v[226:229], v[210:213], v[66:69]
	s_mov_b32 m0, s33
	v_lshl_add_u64 v[162:163], s[28:29], 0, v[150:151]
	s_barrier
	ds_read_b128 v[182:185], v169 offset:16384
	ds_read_b128 v[186:189], v169 offset:17408
	ds_read_b128 v[190:193], v169 offset:18432
	ds_read_b128 v[194:197], v169 offset:19456
	ds_read_b128 v[198:201], v169 offset:20480
	ds_read_b128 v[202:205], v169 offset:21504
	ds_read_b128 v[206:209], v169 offset:22528
	ds_read_b128 v[210:213], v169 offset:23552
	global_load_lds_dwordx4 v150, s[28:29]
	v_lshl_add_u64 v[164:165], s[28:29], 0, v[146:147]
	s_mov_b32 m0, s35
	s_nop 0
	global_load_lds_dwordx4 v146, s[28:29]
	s_barrier
	s_waitcnt lgkmcnt(0)
	v_mfma_f32_16x16x32_bf16 v[62:65], v[156:159], v[182:185], 0
	v_mfma_f32_16x16x32_bf16 v[58:61], v[174:177], v[182:185], 0
	v_mfma_f32_16x16x32_bf16 v[50:53], v[156:159], v[190:193], 0
	v_mfma_f32_16x16x32_bf16 v[42:45], v[174:177], v[190:193], 0
	v_mfma_f32_16x16x32_bf16 v[34:37], v[156:159], v[198:201], 0
	v_mfma_f32_16x16x32_bf16 v[26:29], v[174:177], v[198:201], 0
	v_mfma_f32_16x16x32_bf16 v[18:21], v[156:159], v[206:209], 0
	v_mfma_f32_16x16x32_bf16 v[10:13], v[174:177], v[206:209], 0
	v_mfma_f32_16x16x32_bf16 v[62:65], v[170:173], v[186:189], v[62:65]
	v_mfma_f32_16x16x32_bf16 v[58:61], v[178:181], v[186:189], v[58:61]
	v_mfma_f32_16x16x32_bf16 v[50:53], v[170:173], v[194:197], v[50:53]
	v_mfma_f32_16x16x32_bf16 v[42:45], v[178:181], v[194:197], v[42:45]
	v_mfma_f32_16x16x32_bf16 v[34:37], v[170:173], v[202:205], v[34:37]
	v_mfma_f32_16x16x32_bf16 v[26:29], v[178:181], v[202:205], v[26:29]
	v_mfma_f32_16x16x32_bf16 v[18:21], v[170:173], v[210:213], v[18:21]
	v_mfma_f32_16x16x32_bf16 v[10:13], v[178:181], v[210:213], v[10:13]
	s_barrier
	s_add_u32 s70, s2, 0x40000
	s_addc_u32 s71, s3, 0
	s_add_i32 s72, s72, s23
	s_mov_b32 m0, s72
	s_nop 0
	global_load_lds_dwordx4 v148, s[70:71]
	s_add_i32 m0, s72, 0x2000
	s_nop 0
	global_load_lds_dwordx4 v144, s[70:71]
	s_waitcnt vmcnt(6)
	s_barrier
	v_mfma_f32_16x16x32_bf16 v[54:57], v[214:217], v[182:185], 0
	v_mfma_f32_16x16x32_bf16 v[46:49], v[222:225], v[182:185], 0
	v_mfma_f32_16x16x32_bf16 v[38:41], v[214:217], v[190:193], 0
	v_mfma_f32_16x16x32_bf16 v[30:33], v[222:225], v[190:193], 0
	v_mfma_f32_16x16x32_bf16 v[22:25], v[214:217], v[198:201], 0
	v_mfma_f32_16x16x32_bf16 v[14:17], v[222:225], v[198:201], 0
	v_mfma_f32_16x16x32_bf16 v[6:9], v[214:217], v[206:209], 0
	v_mfma_f32_16x16x32_bf16 v[2:5], v[222:225], v[206:209], 0
	v_mfma_f32_16x16x32_bf16 v[54:57], v[218:221], v[186:189], v[54:57]
	v_mfma_f32_16x16x32_bf16 v[46:49], v[226:229], v[186:189], v[46:49]
	v_mfma_f32_16x16x32_bf16 v[38:41], v[218:221], v[194:197], v[38:41]
	v_mfma_f32_16x16x32_bf16 v[30:33], v[226:229], v[194:197], v[30:33]
	v_mfma_f32_16x16x32_bf16 v[22:25], v[218:221], v[202:205], v[22:25]
	v_mfma_f32_16x16x32_bf16 v[14:17], v[226:229], v[202:205], v[14:17]
	v_mfma_f32_16x16x32_bf16 v[6:9], v[218:221], v[210:213], v[6:9]
	v_mfma_f32_16x16x32_bf16 v[2:5], v[226:229], v[210:213], v[2:5]
	s_add_i32 s70, 0, 0x18000
	v_add_u32_e32 v0, s70, v143
	s_barrier
	ds_read_b128 v[156:159], v0
	ds_read_b128 v[170:173], v0 offset:1024
	ds_read_b128 v[174:177], v0 offset:2048
	ds_read_b128 v[178:181], v0 offset:3072
	s_add_u32 s28, s28, 0x40000
	s_addc_u32 s29, s29, 0
	s_mov_b32 m0, s41
	ds_read_b128 v[182:185], v169 offset:32768
	ds_read_b128 v[186:189], v169 offset:33792
	ds_read_b128 v[190:193], v169 offset:34816
	ds_read_b128 v[194:197], v169 offset:35840
	ds_read_b128 v[198:201], v169 offset:36864
	ds_read_b128 v[202:205], v169 offset:37888
	ds_read_b128 v[206:209], v169 offset:38912
	ds_read_b128 v[210:213], v169 offset:39936
	global_load_lds_dwordx4 v150, s[28:29]
	s_mov_b32 m0, s44
	s_nop 0
	global_load_lds_dwordx4 v146, s[28:29]
	s_waitcnt lgkmcnt(8)
	s_barrier
	s_waitcnt lgkmcnt(0)
	v_mfma_f32_16x16x32_bf16 v[126:129], v[156:159], v[182:185], v[126:129]
	v_mfma_f32_16x16x32_bf16 v[122:125], v[174:177], v[182:185], v[122:125]
	v_mfma_f32_16x16x32_bf16 v[110:113], v[156:159], v[190:193], v[110:113]
	v_mfma_f32_16x16x32_bf16 v[106:109], v[174:177], v[190:193], v[106:109]
	v_mfma_f32_16x16x32_bf16 v[94:97], v[156:159], v[198:201], v[94:97]
	v_mfma_f32_16x16x32_bf16 v[90:93], v[174:177], v[198:201], v[90:93]
	v_mfma_f32_16x16x32_bf16 v[78:81], v[156:159], v[206:209], v[78:81]
	v_mfma_f32_16x16x32_bf16 v[74:77], v[174:177], v[206:209], v[74:77]
	v_mfma_f32_16x16x32_bf16 v[126:129], v[170:173], v[186:189], v[126:129]
	v_mfma_f32_16x16x32_bf16 v[122:125], v[178:181], v[186:189], v[122:125]
	v_mfma_f32_16x16x32_bf16 v[110:113], v[170:173], v[194:197], v[110:113]
	v_mfma_f32_16x16x32_bf16 v[106:109], v[178:181], v[194:197], v[106:109]
	v_mfma_f32_16x16x32_bf16 v[94:97], v[170:173], v[202:205], v[94:97]
	v_mfma_f32_16x16x32_bf16 v[90:93], v[178:181], v[202:205], v[90:93]
	v_mfma_f32_16x16x32_bf16 v[78:81], v[170:173], v[210:213], v[78:81]
	v_mfma_f32_16x16x32_bf16 v[74:77], v[178:181], v[210:213], v[74:77]
	s_barrier
	s_add_i32 s28, 0, 0x1c000
	s_add_i32 s29, s70, s23
	v_add_u32_e32 v0, s28, v143
	s_add_i32 m0, s29, 0xffffff80
	ds_read_b128 v[214:217], v0
	ds_read_b128 v[218:221], v0 offset:1024
	ds_read_b128 v[222:225], v0 offset:2048
	ds_read_b128 v[226:229], v0 offset:3072
	global_load_lds_dwordx4 v148, s[2:3] offset:128
	s_add_i32 m0, s29, 0x1f80
	s_nop 0
	global_load_lds_dwordx4 v144, s[2:3] offset:128
	s_barrier
	s_waitcnt lgkmcnt(0)
	v_mfma_f32_16x16x32_bf16 v[118:121], v[214:217], v[182:185], v[118:121]
	v_mfma_f32_16x16x32_bf16 v[114:117], v[222:225], v[182:185], v[114:117]
	v_mfma_f32_16x16x32_bf16 v[102:105], v[214:217], v[190:193], v[102:105]
	v_mfma_f32_16x16x32_bf16 v[98:101], v[222:225], v[190:193], v[98:101]
	v_mfma_f32_16x16x32_bf16 v[86:89], v[214:217], v[198:201], v[86:89]
	v_mfma_f32_16x16x32_bf16 v[82:85], v[222:225], v[198:201], v[82:85]
	v_mfma_f32_16x16x32_bf16 v[70:73], v[214:217], v[206:209], v[70:73]
	v_mfma_f32_16x16x32_bf16 v[66:69], v[222:225], v[206:209], v[66:69]
	v_mfma_f32_16x16x32_bf16 v[118:121], v[218:221], v[186:189], v[118:121]
	v_mfma_f32_16x16x32_bf16 v[114:117], v[226:229], v[186:189], v[114:117]
	v_mfma_f32_16x16x32_bf16 v[102:105], v[218:221], v[194:197], v[102:105]
	v_mfma_f32_16x16x32_bf16 v[98:101], v[226:229], v[194:197], v[98:101]
	v_mfma_f32_16x16x32_bf16 v[86:89], v[218:221], v[202:205], v[86:89]
	v_mfma_f32_16x16x32_bf16 v[82:85], v[226:229], v[202:205], v[82:85]
	v_mfma_f32_16x16x32_bf16 v[70:73], v[218:221], v[210:213], v[70:73]
	v_mfma_f32_16x16x32_bf16 v[66:69], v[226:229], v[210:213], v[66:69]
	s_mov_b32 m0, s40
	v_lshl_add_u64 v[130:131], v[162:163], 0, s[26:27]
	s_barrier
	ds_read_b128 v[182:185], v169 offset:49152
	ds_read_b128 v[186:189], v169 offset:50176
	ds_read_b128 v[190:193], v169 offset:51200
	ds_read_b128 v[194:197], v169 offset:52224
	ds_read_b128 v[198:201], v169 offset:53248
	ds_read_b128 v[202:205], v169 offset:54272
	ds_read_b128 v[206:209], v169 offset:55296
	ds_read_b128 v[210:213], v169 offset:56320
	global_load_lds_dwordx4 v[130:131], off
	v_lshl_add_u64 v[130:131], v[164:165], 0, s[26:27]
	s_mov_b32 m0, s45
	s_nop 0
	global_load_lds_dwordx4 v[130:131], off
	s_barrier
	s_waitcnt lgkmcnt(0)
	v_mfma_f32_16x16x32_bf16 v[62:65], v[156:159], v[182:185], v[62:65]
	v_mfma_f32_16x16x32_bf16 v[58:61], v[174:177], v[182:185], v[58:61]
	v_mfma_f32_16x16x32_bf16 v[50:53], v[156:159], v[190:193], v[50:53]
	v_mfma_f32_16x16x32_bf16 v[42:45], v[174:177], v[190:193], v[42:45]
	v_mfma_f32_16x16x32_bf16 v[34:37], v[156:159], v[198:201], v[34:37]
	v_mfma_f32_16x16x32_bf16 v[26:29], v[174:177], v[198:201], v[26:29]
	v_mfma_f32_16x16x32_bf16 v[18:21], v[156:159], v[206:209], v[18:21]
	v_mfma_f32_16x16x32_bf16 v[10:13], v[174:177], v[206:209], v[10:13]
	v_mfma_f32_16x16x32_bf16 v[62:65], v[170:173], v[186:189], v[62:65]
	v_mfma_f32_16x16x32_bf16 v[58:61], v[178:181], v[186:189], v[58:61]
	v_mfma_f32_16x16x32_bf16 v[50:53], v[170:173], v[194:197], v[50:53]
	v_mfma_f32_16x16x32_bf16 v[42:45], v[178:181], v[194:197], v[42:45]
	v_mfma_f32_16x16x32_bf16 v[34:37], v[170:173], v[202:205], v[34:37]
	v_mfma_f32_16x16x32_bf16 v[26:29], v[178:181], v[202:205], v[26:29]
	v_mfma_f32_16x16x32_bf16 v[18:21], v[170:173], v[210:213], v[18:21]
	v_mfma_f32_16x16x32_bf16 v[10:13], v[178:181], v[210:213], v[10:13]
	s_barrier
	s_add_u32 s2, s2, 0x40080
	s_addc_u32 s3, s3, 0
	s_add_i32 s28, s28, s23
	s_mov_b32 m0, s28
	s_nop 0
	global_load_lds_dwordx4 v148, s[2:3]
	s_add_i32 m0, s28, 0x2000
	s_nop 0
	global_load_lds_dwordx4 v144, s[2:3]
	s_waitcnt vmcnt(6)
	s_barrier
	v_mfma_f32_16x16x32_bf16 v[54:57], v[214:217], v[182:185], v[54:57]
	v_mfma_f32_16x16x32_bf16 v[46:49], v[222:225], v[182:185], v[46:49]
	v_mfma_f32_16x16x32_bf16 v[38:41], v[214:217], v[190:193], v[38:41]
	v_mfma_f32_16x16x32_bf16 v[30:33], v[222:225], v[190:193], v[30:33]
	v_mfma_f32_16x16x32_bf16 v[22:25], v[214:217], v[198:201], v[22:25]
	v_mfma_f32_16x16x32_bf16 v[14:17], v[222:225], v[198:201], v[14:17]
	v_mfma_f32_16x16x32_bf16 v[6:9], v[214:217], v[206:209], v[6:9]
	v_mfma_f32_16x16x32_bf16 v[2:5], v[222:225], v[206:209], v[2:5]
	v_mfma_f32_16x16x32_bf16 v[54:57], v[218:221], v[186:189], v[54:57]
	v_mfma_f32_16x16x32_bf16 v[46:49], v[226:229], v[186:189], v[46:49]
	v_mfma_f32_16x16x32_bf16 v[38:41], v[218:221], v[194:197], v[38:41]
	v_mfma_f32_16x16x32_bf16 v[30:33], v[226:229], v[194:197], v[30:33]
	v_mfma_f32_16x16x32_bf16 v[22:25], v[218:221], v[202:205], v[22:25]
	v_mfma_f32_16x16x32_bf16 v[14:17], v[226:229], v[202:205], v[14:17]
	v_mfma_f32_16x16x32_bf16 v[6:9], v[218:221], v[210:213], v[6:9]
	v_mfma_f32_16x16x32_bf16 v[2:5], v[226:229], v[210:213], v[2:5]
	s_add_i32 s69, s69, 2
	s_add_u32 s20, s20, 0x100
	s_addc_u32 s21, s21, 0
	s_add_u32 s67, s67, 0x100
	s_addc_u32 s68, s68, 0
	s_cmp_gt_u32 s69, 13
	s_barrier
	s_cbranch_scc0 .LBB0_254
	s_branch .Lafter_254
.LBB0_254:
	s_add_u32 s2, s20, 0xfffc0080
	s_addc_u32 s3, s21, -1
	s_add_i32 s70, 0, 0x10000
	v_add_u32_e32 v0, s70, v143
	ds_read_b128 v[156:159], v0
	ds_read_b128 v[170:173], v0 offset:1024
	ds_read_b128 v[174:177], v0 offset:2048
	ds_read_b128 v[178:181], v0 offset:3072
	s_cmp_eq_u32 s69, 12
	s_cselect_b32 s29, s31, s3
	s_cselect_b32 s28, s65, s2
	s_cselect_b32 s3, s1, s68
	s_cselect_b32 s2, s66, s67
	s_add_i32 m0, s33, 0xc000
	ds_read_b128 v[182:185], v169
	ds_read_b128 v[186:189], v169 offset:1024
	ds_read_b128 v[190:193], v169 offset:2048
	ds_read_b128 v[194:197], v169 offset:3072
	ds_read_b128 v[198:201], v169 offset:4096
	ds_read_b128 v[202:205], v169 offset:5120
	ds_read_b128 v[206:209], v169 offset:6144
	ds_read_b128 v[210:213], v169 offset:7168
	global_load_lds_dwordx4 v152, s[20:21]
	s_add_i32 m0, s33, 0xe000
	s_nop 0
	global_load_lds_dwordx4 v154, s[20:21]
	s_waitcnt lgkmcnt(8)
	s_barrier
	s_waitcnt lgkmcnt(0)
	v_mfma_f32_16x16x32_bf16 v[126:129], v[156:159], v[182:185], v[126:129]
	v_mfma_f32_16x16x32_bf16 v[122:125], v[174:177], v[182:185], v[122:125]
	v_mfma_f32_16x16x32_bf16 v[110:113], v[156:159], v[190:193], v[110:113]
	v_mfma_f32_16x16x32_bf16 v[106:109], v[174:177], v[190:193], v[106:109]
	v_mfma_f32_16x16x32_bf16 v[94:97], v[156:159], v[198:201], v[94:97]
	v_mfma_f32_16x16x32_bf16 v[90:93], v[174:177], v[198:201], v[90:93]
	v_mfma_f32_16x16x32_bf16 v[78:81], v[156:159], v[206:209], v[78:81]
	v_mfma_f32_16x16x32_bf16 v[74:77], v[174:177], v[206:209], v[74:77]
	v_mfma_f32_16x16x32_bf16 v[126:129], v[170:173], v[186:189], v[126:129]
	v_mfma_f32_16x16x32_bf16 v[122:125], v[178:181], v[186:189], v[122:125]
	v_mfma_f32_16x16x32_bf16 v[110:113], v[170:173], v[194:197], v[110:113]
	v_mfma_f32_16x16x32_bf16 v[106:109], v[178:181], v[194:197], v[106:109]
	v_mfma_f32_16x16x32_bf16 v[94:97], v[170:173], v[202:205], v[94:97]
	v_mfma_f32_16x16x32_bf16 v[90:93], v[178:181], v[202:205], v[90:93]
	v_mfma_f32_16x16x32_bf16 v[78:81], v[170:173], v[210:213], v[78:81]
	v_mfma_f32_16x16x32_bf16 v[74:77], v[178:181], v[210:213], v[74:77]
	s_barrier
	s_add_i32 s72, 0, 0x14000
	s_add_i32 s70, s70, s23
	v_add_u32_e32 v0, s72, v143
	s_mov_b32 m0, s70
	ds_read_b128 v[214:217], v0
	ds_read_b128 v[218:221], v0 offset:1024
	ds_read_b128 v[222:225], v0 offset:2048
	ds_read_b128 v[226:229], v0 offset:3072
	global_load_lds_dwordx4 v148, s[2:3]
	s_add_i32 m0, s70, 0x2000
	s_nop 0
	global_load_lds_dwordx4 v144, s[2:3]
	s_barrier
	s_waitcnt lgkmcnt(0)
	v_mfma_f32_16x16x32_bf16 v[118:121], v[214:217], v[182:185], v[118:121]
	v_mfma_f32_16x16x32_bf16 v[114:117], v[222:225], v[182:185], v[114:117]
	v_mfma_f32_16x16x32_bf16 v[102:105], v[214:217], v[190:193], v[102:105]
	v_mfma_f32_16x16x32_bf16 v[98:101], v[222:225], v[190:193], v[98:101]
	v_mfma_f32_16x16x32_bf16 v[86:89], v[214:217], v[198:201], v[86:89]
	v_mfma_f32_16x16x32_bf16 v[82:85], v[222:225], v[198:201], v[82:85]
	v_mfma_f32_16x16x32_bf16 v[70:73], v[214:217], v[206:209], v[70:73]
	v_mfma_f32_16x16x32_bf16 v[66:69], v[222:225], v[206:209], v[66:69]
	v_mfma_f32_16x16x32_bf16 v[118:121], v[218:221], v[186:189], v[118:121]
	v_mfma_f32_16x16x32_bf16 v[114:117], v[226:229], v[186:189], v[114:117]
	v_mfma_f32_16x16x32_bf16 v[102:105], v[218:221], v[194:197], v[102:105]
	v_mfma_f32_16x16x32_bf16 v[98:101], v[226:229], v[194:197], v[98:101]
	v_mfma_f32_16x16x32_bf16 v[86:89], v[218:221], v[202:205], v[86:89]
	v_mfma_f32_16x16x32_bf16 v[82:85], v[226:229], v[202:205], v[82:85]
	v_mfma_f32_16x16x32_bf16 v[70:73], v[218:221], v[210:213], v[70:73]
	v_mfma_f32_16x16x32_bf16 v[66:69], v[226:229], v[210:213], v[66:69]
	s_mov_b32 m0, s33
	v_lshl_add_u64 v[162:163], s[28:29], 0, v[150:151]
	s_barrier
	ds_read_b128 v[182:185], v169 offset:16384
	ds_read_b128 v[186:189], v169 offset:17408
	ds_read_b128 v[190:193], v169 offset:18432
	ds_read_b128 v[194:197], v169 offset:19456
	ds_read_b128 v[198:201], v169 offset:20480
	ds_read_b128 v[202:205], v169 offset:21504
	ds_read_b128 v[206:209], v169 offset:22528
	ds_read_b128 v[210:213], v169 offset:23552
	global_load_lds_dwordx4 v150, s[28:29]
	v_lshl_add_u64 v[164:165], s[28:29], 0, v[146:147]
	s_mov_b32 m0, s35
	s_nop 0
	global_load_lds_dwordx4 v146, s[28:29]
	s_barrier
	s_waitcnt lgkmcnt(0)
	v_mfma_f32_16x16x32_bf16 v[62:65], v[156:159], v[182:185], v[62:65]
	v_mfma_f32_16x16x32_bf16 v[58:61], v[174:177], v[182:185], v[58:61]
	v_mfma_f32_16x16x32_bf16 v[50:53], v[156:159], v[190:193], v[50:53]
	v_mfma_f32_16x16x32_bf16 v[42:45], v[174:177], v[190:193], v[42:45]
	v_mfma_f32_16x16x32_bf16 v[34:37], v[156:159], v[198:201], v[34:37]
	v_mfma_f32_16x16x32_bf16 v[26:29], v[174:177], v[198:201], v[26:29]
	v_mfma_f32_16x16x32_bf16 v[18:21], v[156:159], v[206:209], v[18:21]
	v_mfma_f32_16x16x32_bf16 v[10:13], v[174:177], v[206:209], v[10:13]
	v_mfma_f32_16x16x32_bf16 v[62:65], v[170:173], v[186:189], v[62:65]
	v_mfma_f32_16x16x32_bf16 v[58:61], v[178:181], v[186:189], v[58:61]
	v_mfma_f32_16x16x32_bf16 v[50:53], v[170:173], v[194:197], v[50:53]
	v_mfma_f32_16x16x32_bf16 v[42:45], v[178:181], v[194:197], v[42:45]
	v_mfma_f32_16x16x32_bf16 v[34:37], v[170:173], v[202:205], v[34:37]
	v_mfma_f32_16x16x32_bf16 v[26:29], v[178:181], v[202:205], v[26:29]
	v_mfma_f32_16x16x32_bf16 v[18:21], v[170:173], v[210:213], v[18:21]
	v_mfma_f32_16x16x32_bf16 v[10:13], v[178:181], v[210:213], v[10:13]
	s_barrier
	s_add_u32 s70, s2, 0x40000
	s_addc_u32 s71, s3, 0
	s_add_i32 s72, s72, s23
	s_mov_b32 m0, s72
	s_nop 0
	global_load_lds_dwordx4 v148, s[70:71]
	s_add_i32 m0, s72, 0x2000
	s_nop 0
	global_load_lds_dwordx4 v144, s[70:71]
	s_waitcnt vmcnt(6)
	s_barrier
	v_mfma_f32_16x16x32_bf16 v[54:57], v[214:217], v[182:185], v[54:57]
	v_mfma_f32_16x16x32_bf16 v[46:49], v[222:225], v[182:185], v[46:49]
	v_mfma_f32_16x16x32_bf16 v[38:41], v[214:217], v[190:193], v[38:41]
	v_mfma_f32_16x16x32_bf16 v[30:33], v[222:225], v[190:193], v[30:33]
	v_mfma_f32_16x16x32_bf16 v[22:25], v[214:217], v[198:201], v[22:25]
	v_mfma_f32_16x16x32_bf16 v[14:17], v[222:225], v[198:201], v[14:17]
	v_mfma_f32_16x16x32_bf16 v[6:9], v[214:217], v[206:209], v[6:9]
	v_mfma_f32_16x16x32_bf16 v[2:5], v[222:225], v[206:209], v[2:5]
	v_mfma_f32_16x16x32_bf16 v[54:57], v[218:221], v[186:189], v[54:57]
	v_mfma_f32_16x16x32_bf16 v[46:49], v[226:229], v[186:189], v[46:49]
	v_mfma_f32_16x16x32_bf16 v[38:41], v[218:221], v[194:197], v[38:41]
	v_mfma_f32_16x16x32_bf16 v[30:33], v[226:229], v[194:197], v[30:33]
	v_mfma_f32_16x16x32_bf16 v[22:25], v[218:221], v[202:205], v[22:25]
	v_mfma_f32_16x16x32_bf16 v[14:17], v[226:229], v[202:205], v[14:17]
	v_mfma_f32_16x16x32_bf16 v[6:9], v[218:221], v[210:213], v[6:9]
	v_mfma_f32_16x16x32_bf16 v[2:5], v[226:229], v[210:213], v[2:5]
	s_add_i32 s70, 0, 0x18000
	v_add_u32_e32 v0, s70, v143
	s_barrier
	ds_read_b128 v[156:159], v0
	ds_read_b128 v[170:173], v0 offset:1024
	ds_read_b128 v[174:177], v0 offset:2048
	ds_read_b128 v[178:181], v0 offset:3072
	s_add_u32 s28, s28, 0x40000
	s_addc_u32 s29, s29, 0
	s_mov_b32 m0, s41
	ds_read_b128 v[182:185], v169 offset:32768
	ds_read_b128 v[186:189], v169 offset:33792
	ds_read_b128 v[190:193], v169 offset:34816
	ds_read_b128 v[194:197], v169 offset:35840
	ds_read_b128 v[198:201], v169 offset:36864
	ds_read_b128 v[202:205], v169 offset:37888
	ds_read_b128 v[206:209], v169 offset:38912
	ds_read_b128 v[210:213], v169 offset:39936
	global_load_lds_dwordx4 v150, s[28:29]
	s_mov_b32 m0, s44
	s_nop 0
	global_load_lds_dwordx4 v146, s[28:29]
	s_waitcnt lgkmcnt(8)
	s_barrier
	s_waitcnt lgkmcnt(0)
	v_mfma_f32_16x16x32_bf16 v[126:129], v[156:159], v[182:185], v[126:129]
	v_mfma_f32_16x16x32_bf16 v[122:125], v[174:177], v[182:185], v[122:125]
	v_mfma_f32_16x16x32_bf16 v[110:113], v[156:159], v[190:193], v[110:113]
	v_mfma_f32_16x16x32_bf16 v[106:109], v[174:177], v[190:193], v[106:109]
	v_mfma_f32_16x16x32_bf16 v[94:97], v[156:159], v[198:201], v[94:97]
	v_mfma_f32_16x16x32_bf16 v[90:93], v[174:177], v[198:201], v[90:93]
	v_mfma_f32_16x16x32_bf16 v[78:81], v[156:159], v[206:209], v[78:81]
	v_mfma_f32_16x16x32_bf16 v[74:77], v[174:177], v[206:209], v[74:77]
	v_mfma_f32_16x16x32_bf16 v[126:129], v[170:173], v[186:189], v[126:129]
	v_mfma_f32_16x16x32_bf16 v[122:125], v[178:181], v[186:189], v[122:125]
	v_mfma_f32_16x16x32_bf16 v[110:113], v[170:173], v[194:197], v[110:113]
	v_mfma_f32_16x16x32_bf16 v[106:109], v[178:181], v[194:197], v[106:109]
	v_mfma_f32_16x16x32_bf16 v[94:97], v[170:173], v[202:205], v[94:97]
	v_mfma_f32_16x16x32_bf16 v[90:93], v[178:181], v[202:205], v[90:93]
	v_mfma_f32_16x16x32_bf16 v[78:81], v[170:173], v[210:213], v[78:81]
	v_mfma_f32_16x16x32_bf16 v[74:77], v[178:181], v[210:213], v[74:77]
	s_barrier
	s_add_i32 s28, 0, 0x1c000
	s_add_i32 s29, s70, s23
	v_add_u32_e32 v0, s28, v143
	s_add_i32 m0, s29, 0xffffff80
	ds_read_b128 v[214:217], v0
	ds_read_b128 v[218:221], v0 offset:1024
	ds_read_b128 v[222:225], v0 offset:2048
	ds_read_b128 v[226:229], v0 offset:3072
	global_load_lds_dwordx4 v148, s[2:3] offset:128
	s_add_i32 m0, s29, 0x1f80
	s_nop 0
	global_load_lds_dwordx4 v144, s[2:3] offset:128
	s_barrier
	s_waitcnt lgkmcnt(0)
	v_mfma_f32_16x16x32_bf16 v[118:121], v[214:217], v[182:185], v[118:121]
	v_mfma_f32_16x16x32_bf16 v[114:117], v[222:225], v[182:185], v[114:117]
	v_mfma_f32_16x16x32_bf16 v[102:105], v[214:217], v[190:193], v[102:105]
	v_mfma_f32_16x16x32_bf16 v[98:101], v[222:225], v[190:193], v[98:101]
	v_mfma_f32_16x16x32_bf16 v[86:89], v[214:217], v[198:201], v[86:89]
	v_mfma_f32_16x16x32_bf16 v[82:85], v[222:225], v[198:201], v[82:85]
	v_mfma_f32_16x16x32_bf16 v[70:73], v[214:217], v[206:209], v[70:73]
	v_mfma_f32_16x16x32_bf16 v[66:69], v[222:225], v[206:209], v[66:69]
	v_mfma_f32_16x16x32_bf16 v[118:121], v[218:221], v[186:189], v[118:121]
	v_mfma_f32_16x16x32_bf16 v[114:117], v[226:229], v[186:189], v[114:117]
	v_mfma_f32_16x16x32_bf16 v[102:105], v[218:221], v[194:197], v[102:105]
	v_mfma_f32_16x16x32_bf16 v[98:101], v[226:229], v[194:197], v[98:101]
	v_mfma_f32_16x16x32_bf16 v[86:89], v[218:221], v[202:205], v[86:89]
	v_mfma_f32_16x16x32_bf16 v[82:85], v[226:229], v[202:205], v[82:85]
	v_mfma_f32_16x16x32_bf16 v[70:73], v[218:221], v[210:213], v[70:73]
	v_mfma_f32_16x16x32_bf16 v[66:69], v[226:229], v[210:213], v[66:69]
	s_mov_b32 m0, s40
	v_lshl_add_u64 v[130:131], v[162:163], 0, s[26:27]
	s_barrier
	ds_read_b128 v[182:185], v169 offset:49152
	ds_read_b128 v[186:189], v169 offset:50176
	ds_read_b128 v[190:193], v169 offset:51200
	ds_read_b128 v[194:197], v169 offset:52224
	ds_read_b128 v[198:201], v169 offset:53248
	ds_read_b128 v[202:205], v169 offset:54272
	ds_read_b128 v[206:209], v169 offset:55296
	ds_read_b128 v[210:213], v169 offset:56320
	global_load_lds_dwordx4 v[130:131], off
	v_lshl_add_u64 v[130:131], v[164:165], 0, s[26:27]
	s_mov_b32 m0, s45
	s_nop 0
	global_load_lds_dwordx4 v[130:131], off
	s_barrier
	s_waitcnt lgkmcnt(0)
	v_mfma_f32_16x16x32_bf16 v[62:65], v[156:159], v[182:185], v[62:65]
	v_mfma_f32_16x16x32_bf16 v[58:61], v[174:177], v[182:185], v[58:61]
	v_mfma_f32_16x16x32_bf16 v[50:53], v[156:159], v[190:193], v[50:53]
	v_mfma_f32_16x16x32_bf16 v[42:45], v[174:177], v[190:193], v[42:45]
	v_mfma_f32_16x16x32_bf16 v[34:37], v[156:159], v[198:201], v[34:37]
	v_mfma_f32_16x16x32_bf16 v[26:29], v[174:177], v[198:201], v[26:29]
	v_mfma_f32_16x16x32_bf16 v[18:21], v[156:159], v[206:209], v[18:21]
	v_mfma_f32_16x16x32_bf16 v[10:13], v[174:177], v[206:209], v[10:13]
	v_mfma_f32_16x16x32_bf16 v[62:65], v[170:173], v[186:189], v[62:65]
	v_mfma_f32_16x16x32_bf16 v[58:61], v[178:181], v[186:189], v[58:61]
	v_mfma_f32_16x16x32_bf16 v[50:53], v[170:173], v[194:197], v[50:53]
	v_mfma_f32_16x16x32_bf16 v[42:45], v[178:181], v[194:197], v[42:45]
	v_mfma_f32_16x16x32_bf16 v[34:37], v[170:173], v[202:205], v[34:37]
	v_mfma_f32_16x16x32_bf16 v[26:29], v[178:181], v[202:205], v[26:29]
	v_mfma_f32_16x16x32_bf16 v[18:21], v[170:173], v[210:213], v[18:21]
	v_mfma_f32_16x16x32_bf16 v[10:13], v[178:181], v[210:213], v[10:13]
	s_barrier
	s_add_u32 s2, s2, 0x40080
	s_addc_u32 s3, s3, 0
	s_add_i32 s28, s28, s23
	s_mov_b32 m0, s28
	s_nop 0
	global_load_lds_dwordx4 v148, s[2:3]
	s_add_i32 m0, s28, 0x2000
	s_nop 0
	global_load_lds_dwordx4 v144, s[2:3]
	s_waitcnt vmcnt(6)
	s_barrier
	v_mfma_f32_16x16x32_bf16 v[54:57], v[214:217], v[182:185], v[54:57]
	v_mfma_f32_16x16x32_bf16 v[46:49], v[222:225], v[182:185], v[46:49]
	v_mfma_f32_16x16x32_bf16 v[38:41], v[214:217], v[190:193], v[38:41]
	v_mfma_f32_16x16x32_bf16 v[30:33], v[222:225], v[190:193], v[30:33]
	v_mfma_f32_16x16x32_bf16 v[22:25], v[214:217], v[198:201], v[22:25]
	v_mfma_f32_16x16x32_bf16 v[14:17], v[222:225], v[198:201], v[14:17]
	v_mfma_f32_16x16x32_bf16 v[6:9], v[214:217], v[206:209], v[6:9]
	v_mfma_f32_16x16x32_bf16 v[2:5], v[222:225], v[206:209], v[2:5]
	v_mfma_f32_16x16x32_bf16 v[54:57], v[218:221], v[186:189], v[54:57]
	v_mfma_f32_16x16x32_bf16 v[46:49], v[226:229], v[186:189], v[46:49]
	v_mfma_f32_16x16x32_bf16 v[38:41], v[218:221], v[194:197], v[38:41]
	v_mfma_f32_16x16x32_bf16 v[30:33], v[226:229], v[194:197], v[30:33]
	v_mfma_f32_16x16x32_bf16 v[22:25], v[218:221], v[202:205], v[22:25]
	v_mfma_f32_16x16x32_bf16 v[14:17], v[226:229], v[202:205], v[14:17]
	v_mfma_f32_16x16x32_bf16 v[6:9], v[218:221], v[210:213], v[6:9]
	v_mfma_f32_16x16x32_bf16 v[2:5], v[226:229], v[210:213], v[2:5]
	s_add_i32 s69, s69, 2
	s_add_u32 s20, s20, 0x100
	s_addc_u32 s21, s21, 0
	s_add_u32 s67, s67, 0x100
	s_addc_u32 s68, s68, 0
	s_cmp_gt_u32 s69, 13
	s_barrier
	s_cbranch_scc0 .LBB0_254

.LBB0_317:
	s_add_i32 s22, s68, -2
	s_add_u32 vcc_lo, s2, 0x80
	s_addc_u32 vcc_hi, s3, 0
	s_add_u32 s23, s98, 0x100
	s_addc_u32 s47, s99, 0
	s_mov_b32 s2, 0
	s_waitcnt lgkmcnt(0)
	s_add_i32 s71, s2, 2
	s_add_u32 s98, vcc_lo, 0x80
	s_addc_u32 s3, vcc_hi, 0
	s_add_i32 s73, 0, 0x10000
	v_add_u32_e32 v0, s73, v143
	ds_read_b128 v[168:171], v0
	ds_read_b128 v[172:175], v0 offset:1024
	ds_read_b128 v[176:179], v0 offset:2048
	ds_read_b128 v[180:183], v0 offset:3072
	s_cmp_eq_u32 s22, s2
	s_cselect_b32 s2, s20, s98
	s_cselect_b32 s3, s21, s3
	s_cselect_b32 s99, s1, s47
	s_cselect_b32 s98, s0, s23
	s_add_i32 m0, s43, 0xc000
	ds_read_b128 v[184:187], v159
	ds_read_b128 v[188:191], v159 offset:1024
	ds_read_b128 v[192:195], v159 offset:2048
	ds_read_b128 v[196:199], v159 offset:3072
	ds_read_b128 v[200:203], v159 offset:4096
	ds_read_b128 v[204:207], v159 offset:5120
	ds_read_b128 v[208:211], v159 offset:6144
	ds_read_b128 v[212:215], v159 offset:7168
	global_load_lds_dwordx4 v152, vcc
	s_add_i32 m0, s43, 0xe000
	s_nop 0
	global_load_lds_dwordx4 v154, vcc
	s_waitcnt lgkmcnt(8)
	s_barrier
	s_waitcnt lgkmcnt(0)
	v_mfma_f32_16x16x32_bf16 v[126:129], v[168:171], v[184:187], 0
	v_mfma_f32_16x16x32_bf16 v[122:125], v[176:179], v[184:187], 0
	v_mfma_f32_16x16x32_bf16 v[118:121], v[168:171], v[192:195], 0
	v_mfma_f32_16x16x32_bf16 v[110:113], v[176:179], v[192:195], 0
	v_mfma_f32_16x16x32_bf16 v[102:105], v[168:171], v[200:203], 0
	v_mfma_f32_16x16x32_bf16 v[94:97], v[176:179], v[200:203], 0
	v_mfma_f32_16x16x32_bf16 v[86:89], v[168:171], v[208:211], 0
	v_mfma_f32_16x16x32_bf16 v[78:81], v[176:179], v[208:211], 0
	v_mfma_f32_16x16x32_bf16 v[126:129], v[172:175], v[188:191], v[126:129]
	v_mfma_f32_16x16x32_bf16 v[122:125], v[180:183], v[188:191], v[122:125]
	v_mfma_f32_16x16x32_bf16 v[118:121], v[172:175], v[196:199], v[118:121]
	v_mfma_f32_16x16x32_bf16 v[110:113], v[180:183], v[196:199], v[110:113]
	v_mfma_f32_16x16x32_bf16 v[102:105], v[172:175], v[204:207], v[102:105]
	v_mfma_f32_16x16x32_bf16 v[94:97], v[180:183], v[204:207], v[94:97]
	v_mfma_f32_16x16x32_bf16 v[86:89], v[172:175], v[212:215], v[86:89]
	v_mfma_f32_16x16x32_bf16 v[78:81], v[180:183], v[212:215], v[78:81]
	s_barrier
	s_add_i32 s70, 0, 0x14000
	s_add_i32 s73, s73, s41
	v_add_u32_e32 v0, s70, v143
	v_lshl_add_u64 v[130:131], s[98:99], 0, v[146:147]
	s_mov_b32 m0, s73
	ds_read_b128 v[216:219], v0
	ds_read_b128 v[220:223], v0 offset:1024
	ds_read_b128 v[224:227], v0 offset:2048
	ds_read_b128 v[228:231], v0 offset:3072
	global_load_lds_dwordx4 v146, s[98:99]
	v_lshl_add_u64 v[132:133], s[98:99], 0, v[150:151]
	s_add_i32 m0, s73, 0x2000
	s_nop 0
	global_load_lds_dwordx4 v150, s[98:99]
	s_barrier
	s_waitcnt lgkmcnt(0)
	v_mfma_f32_16x16x32_bf16 v[114:117], v[216:219], v[184:187], 0
	v_mfma_f32_16x16x32_bf16 v[106:109], v[224:227], v[184:187], 0
	v_mfma_f32_16x16x32_bf16 v[98:101], v[216:219], v[192:195], 0
	v_mfma_f32_16x16x32_bf16 v[90:93], v[224:227], v[192:195], 0
	v_mfma_f32_16x16x32_bf16 v[82:85], v[216:219], v[200:203], 0
	v_mfma_f32_16x16x32_bf16 v[74:77], v[224:227], v[200:203], 0
	v_mfma_f32_16x16x32_bf16 v[70:73], v[216:219], v[208:211], 0
	v_mfma_f32_16x16x32_bf16 v[66:69], v[224:227], v[208:211], 0
	v_mfma_f32_16x16x32_bf16 v[114:117], v[220:223], v[188:191], v[114:117]
	v_mfma_f32_16x16x32_bf16 v[106:109], v[228:231], v[188:191], v[106:109]
	v_mfma_f32_16x16x32_bf16 v[98:101], v[220:223], v[196:199], v[98:101]
	v_mfma_f32_16x16x32_bf16 v[90:93], v[228:231], v[196:199], v[90:93]
	v_mfma_f32_16x16x32_bf16 v[82:85], v[220:223], v[204:207], v[82:85]
	v_mfma_f32_16x16x32_bf16 v[74:77], v[228:231], v[204:207], v[74:77]
	v_mfma_f32_16x16x32_bf16 v[70:73], v[220:223], v[212:215], v[70:73]
	v_mfma_f32_16x16x32_bf16 v[66:69], v[228:231], v[212:215], v[66:69]
	s_mov_b32 m0, s43
	v_lshl_add_u64 v[156:157], s[2:3], 0, v[144:145]
	s_barrier
	ds_read_b128 v[184:187], v159 offset:16384
	ds_read_b128 v[188:191], v159 offset:17408
	ds_read_b128 v[192:195], v159 offset:18432
	ds_read_b128 v[196:199], v159 offset:19456
	ds_read_b128 v[200:203], v159 offset:20480
	ds_read_b128 v[204:207], v159 offset:21504
	ds_read_b128 v[208:211], v159 offset:22528
	ds_read_b128 v[212:215], v159 offset:23552
	global_load_lds_dwordx4 v144, s[2:3]
	v_lshl_add_u64 v[162:163], s[2:3], 0, v[148:149]
	s_mov_b32 m0, s44
	s_nop 0
	global_load_lds_dwordx4 v148, s[2:3]
	s_barrier
	s_waitcnt lgkmcnt(0)
	v_mfma_f32_16x16x32_bf16 v[62:65], v[168:171], v[184:187], 0
	v_mfma_f32_16x16x32_bf16 v[58:61], v[176:179], v[184:187], 0
	v_mfma_f32_16x16x32_bf16 v[54:57], v[168:171], v[192:195], 0
	v_mfma_f32_16x16x32_bf16 v[46:49], v[176:179], v[192:195], 0
	v_mfma_f32_16x16x32_bf16 v[38:41], v[168:171], v[200:203], 0
	v_mfma_f32_16x16x32_bf16 v[30:33], v[176:179], v[200:203], 0
	v_mfma_f32_16x16x32_bf16 v[22:25], v[168:171], v[208:211], 0
	v_mfma_f32_16x16x32_bf16 v[14:17], v[176:179], v[208:211], 0
	v_mfma_f32_16x16x32_bf16 v[62:65], v[172:175], v[188:191], v[62:65]
	v_mfma_f32_16x16x32_bf16 v[58:61], v[180:183], v[188:191], v[58:61]
	v_mfma_f32_16x16x32_bf16 v[54:57], v[172:175], v[196:199], v[54:57]
	v_mfma_f32_16x16x32_bf16 v[46:49], v[180:183], v[196:199], v[46:49]
	v_mfma_f32_16x16x32_bf16 v[38:41], v[172:175], v[204:207], v[38:41]
	v_mfma_f32_16x16x32_bf16 v[30:33], v[180:183], v[204:207], v[30:33]
	v_mfma_f32_16x16x32_bf16 v[22:25], v[172:175], v[212:215], v[22:25]
	v_mfma_f32_16x16x32_bf16 v[14:17], v[180:183], v[212:215], v[14:17]
	s_barrier
	s_add_u32 s98, s98, s96
	s_addc_u32 s99, s99, 0
	s_add_i32 s70, s70, s41
	s_mov_b32 m0, s70
	s_nop 0
	global_load_lds_dwordx4 v146, s[98:99]
	s_add_i32 m0, s70, 0x2000
	s_nop 0
	global_load_lds_dwordx4 v150, s[98:99]
	s_waitcnt vmcnt(6)
	s_barrier
	v_mfma_f32_16x16x32_bf16 v[50:53], v[216:219], v[184:187], 0
	v_mfma_f32_16x16x32_bf16 v[42:45], v[224:227], v[184:187], 0
	v_mfma_f32_16x16x32_bf16 v[34:37], v[216:219], v[192:195], 0
	v_mfma_f32_16x16x32_bf16 v[26:29], v[224:227], v[192:195], 0
	v_mfma_f32_16x16x32_bf16 v[18:21], v[216:219], v[200:203], 0
	v_mfma_f32_16x16x32_bf16 v[10:13], v[224:227], v[200:203], 0
	v_mfma_f32_16x16x32_bf16 v[6:9], v[216:219], v[208:211], 0
	v_mfma_f32_16x16x32_bf16 v[2:5], v[224:227], v[208:211], 0
	v_mfma_f32_16x16x32_bf16 v[50:53], v[220:223], v[188:191], v[50:53]
	v_mfma_f32_16x16x32_bf16 v[42:45], v[228:231], v[188:191], v[42:45]
	v_mfma_f32_16x16x32_bf16 v[34:37], v[220:223], v[196:199], v[34:37]
	v_mfma_f32_16x16x32_bf16 v[26:29], v[228:231], v[196:199], v[26:29]
	v_mfma_f32_16x16x32_bf16 v[18:21], v[220:223], v[204:207], v[18:21]
	v_mfma_f32_16x16x32_bf16 v[10:13], v[228:231], v[204:207], v[10:13]
	v_mfma_f32_16x16x32_bf16 v[6:9], v[220:223], v[212:215], v[6:9]
	v_mfma_f32_16x16x32_bf16 v[2:5], v[228:231], v[212:215], v[2:5]
	s_add_i32 s70, 0, 0x18000
	v_add_u32_e32 v0, s70, v143
	s_barrier
	ds_read_b128 v[168:171], v0
	ds_read_b128 v[172:175], v0 offset:1024
	ds_read_b128 v[176:179], v0 offset:2048
	ds_read_b128 v[180:183], v0 offset:3072
	s_add_u32 s2, s2, s96
	s_addc_u32 s3, s3, 0
	s_mov_b32 m0, s45
	ds_read_b128 v[184:187], v159 offset:32768
	ds_read_b128 v[188:191], v159 offset:33792
	ds_read_b128 v[192:195], v159 offset:34816
	ds_read_b128 v[196:199], v159 offset:35840
	ds_read_b128 v[200:203], v159 offset:36864
	ds_read_b128 v[204:207], v159 offset:37888
	ds_read_b128 v[208:211], v159 offset:38912
	ds_read_b128 v[212:215], v159 offset:39936
	global_load_lds_dwordx4 v144, s[2:3]
	s_mov_b32 m0, s40
	s_nop 0
	global_load_lds_dwordx4 v148, s[2:3]
	s_waitcnt lgkmcnt(8)
	s_barrier
	s_waitcnt lgkmcnt(0)
	v_mfma_f32_16x16x32_bf16 v[126:129], v[168:171], v[184:187], v[126:129]
	v_mfma_f32_16x16x32_bf16 v[122:125], v[176:179], v[184:187], v[122:125]
	v_mfma_f32_16x16x32_bf16 v[118:121], v[168:171], v[192:195], v[118:121]
	v_mfma_f32_16x16x32_bf16 v[110:113], v[176:179], v[192:195], v[110:113]
	v_mfma_f32_16x16x32_bf16 v[102:105], v[168:171], v[200:203], v[102:105]
	v_mfma_f32_16x16x32_bf16 v[94:97], v[176:179], v[200:203], v[94:97]
	v_mfma_f32_16x16x32_bf16 v[86:89], v[168:171], v[208:211], v[86:89]
	v_mfma_f32_16x16x32_bf16 v[78:81], v[176:179], v[208:211], v[78:81]
	v_mfma_f32_16x16x32_bf16 v[126:129], v[172:175], v[188:191], v[126:129]
	v_mfma_f32_16x16x32_bf16 v[122:125], v[180:183], v[188:191], v[122:125]
	v_mfma_f32_16x16x32_bf16 v[118:121], v[172:175], v[196:199], v[118:121]
	v_mfma_f32_16x16x32_bf16 v[110:113], v[180:183], v[196:199], v[110:113]
	v_mfma_f32_16x16x32_bf16 v[102:105], v[172:175], v[204:207], v[102:105]
	v_mfma_f32_16x16x32_bf16 v[94:97], v[180:183], v[204:207], v[94:97]
	v_mfma_f32_16x16x32_bf16 v[86:89], v[172:175], v[212:215], v[86:89]
	v_mfma_f32_16x16x32_bf16 v[78:81], v[180:183], v[212:215], v[78:81]
	s_barrier
	s_add_i32 s2, 0, 0x1c000
	s_add_i32 s3, s70, s41
	v_add_u32_e32 v0, s2, v143
	v_lshl_add_u64 v[130:131], v[130:131], 0, s[26:27]
	s_mov_b32 m0, s3
	ds_read_b128 v[216:219], v0
	ds_read_b128 v[220:223], v0 offset:1024
	ds_read_b128 v[224:227], v0 offset:2048
	ds_read_b128 v[228:231], v0 offset:3072
	global_load_lds_dwordx4 v[130:131], off
	v_lshl_add_u64 v[130:131], v[132:133], 0, s[26:27]
	s_add_i32 m0, s3, 0x2000
	s_nop 0
	global_load_lds_dwordx4 v[130:131], off
	s_barrier
	s_waitcnt lgkmcnt(0)
	v_mfma_f32_16x16x32_bf16 v[114:117], v[216:219], v[184:187], v[114:117]
	v_mfma_f32_16x16x32_bf16 v[106:109], v[224:227], v[184:187], v[106:109]
	v_mfma_f32_16x16x32_bf16 v[98:101], v[216:219], v[192:195], v[98:101]
	v_mfma_f32_16x16x32_bf16 v[90:93], v[224:227], v[192:195], v[90:93]
	v_mfma_f32_16x16x32_bf16 v[82:85], v[216:219], v[200:203], v[82:85]
	v_mfma_f32_16x16x32_bf16 v[74:77], v[224:227], v[200:203], v[74:77]
	v_mfma_f32_16x16x32_bf16 v[70:73], v[216:219], v[208:211], v[70:73]
	v_mfma_f32_16x16x32_bf16 v[66:69], v[224:227], v[208:211], v[66:69]
	v_mfma_f32_16x16x32_bf16 v[114:117], v[220:223], v[188:191], v[114:117]
	v_mfma_f32_16x16x32_bf16 v[106:109], v[228:231], v[188:191], v[106:109]
	v_mfma_f32_16x16x32_bf16 v[98:101], v[220:223], v[196:199], v[98:101]
	v_mfma_f32_16x16x32_bf16 v[90:93], v[228:231], v[196:199], v[90:93]
	v_mfma_f32_16x16x32_bf16 v[82:85], v[220:223], v[204:207], v[82:85]
	v_mfma_f32_16x16x32_bf16 v[74:77], v[228:231], v[204:207], v[74:77]
	v_mfma_f32_16x16x32_bf16 v[70:73], v[220:223], v[212:215], v[70:73]
	v_mfma_f32_16x16x32_bf16 v[66:69], v[228:231], v[212:215], v[66:69]
	s_mov_b32 m0, s66
	v_lshl_add_u64 v[130:131], v[156:157], 0, s[26:27]
	s_barrier
	ds_read_b128 v[184:187], v159 offset:49152
	ds_read_b128 v[188:191], v159 offset:50176
	ds_read_b128 v[192:195], v159 offset:51200
	ds_read_b128 v[196:199], v159 offset:52224
	ds_read_b128 v[200:203], v159 offset:53248
	ds_read_b128 v[204:207], v159 offset:54272
	ds_read_b128 v[208:211], v159 offset:55296
	ds_read_b128 v[212:215], v159 offset:56320
	global_load_lds_dwordx4 v[130:131], off
	v_lshl_add_u64 v[130:131], v[162:163], 0, s[26:27]
	s_mov_b32 m0, s67
	s_nop 0
	global_load_lds_dwordx4 v[130:131], off
	s_barrier
	s_waitcnt lgkmcnt(0)
	v_mfma_f32_16x16x32_bf16 v[62:65], v[168:171], v[184:187], v[62:65]
	v_mfma_f32_16x16x32_bf16 v[58:61], v[176:179], v[184:187], v[58:61]
	v_mfma_f32_16x16x32_bf16 v[54:57], v[168:171], v[192:195], v[54:57]
	v_mfma_f32_16x16x32_bf16 v[46:49], v[176:179], v[192:195], v[46:49]
	v_mfma_f32_16x16x32_bf16 v[38:41], v[168:171], v[200:203], v[38:41]
	v_mfma_f32_16x16x32_bf16 v[30:33], v[176:179], v[200:203], v[30:33]
	v_mfma_f32_16x16x32_bf16 v[22:25], v[168:171], v[208:211], v[22:25]
	v_mfma_f32_16x16x32_bf16 v[14:17], v[176:179], v[208:211], v[14:17]
	v_mfma_f32_16x16x32_bf16 v[62:65], v[172:175], v[188:191], v[62:65]
	v_mfma_f32_16x16x32_bf16 v[58:61], v[180:183], v[188:191], v[58:61]
	v_mfma_f32_16x16x32_bf16 v[54:57], v[172:175], v[196:199], v[54:57]
	v_mfma_f32_16x16x32_bf16 v[46:49], v[180:183], v[196:199], v[46:49]
	v_mfma_f32_16x16x32_bf16 v[38:41], v[172:175], v[204:207], v[38:41]
	v_mfma_f32_16x16x32_bf16 v[30:33], v[180:183], v[204:207], v[30:33]
	v_mfma_f32_16x16x32_bf16 v[22:25], v[172:175], v[212:215], v[22:25]
	v_mfma_f32_16x16x32_bf16 v[14:17], v[180:183], v[212:215], v[14:17]
	s_barrier
	s_add_i32 s2, s2, s41
	s_add_i32 m0, s2, 0xffffff80
	s_nop 0
	global_load_lds_dwordx4 v146, s[98:99] offset:128
	s_add_i32 m0, s2, 0x1f80
	s_nop 0
	global_load_lds_dwordx4 v150, s[98:99] offset:128
	s_waitcnt vmcnt(6)
	s_barrier
	v_mfma_f32_16x16x32_bf16 v[50:53], v[216:219], v[184:187], v[50:53]
	v_mfma_f32_16x16x32_bf16 v[42:45], v[224:227], v[184:187], v[42:45]
	v_mfma_f32_16x16x32_bf16 v[34:37], v[216:219], v[192:195], v[34:37]
	v_mfma_f32_16x16x32_bf16 v[26:29], v[224:227], v[192:195], v[26:29]
	v_mfma_f32_16x16x32_bf16 v[18:21], v[216:219], v[200:203], v[18:21]
	v_mfma_f32_16x16x32_bf16 v[10:13], v[224:227], v[200:203], v[10:13]
	v_mfma_f32_16x16x32_bf16 v[6:9], v[216:219], v[208:211], v[6:9]
	v_mfma_f32_16x16x32_bf16 v[2:5], v[224:227], v[208:211], v[2:5]
	v_mfma_f32_16x16x32_bf16 v[50:53], v[220:223], v[188:191], v[50:53]
	v_mfma_f32_16x16x32_bf16 v[42:45], v[228:231], v[188:191], v[42:45]
	v_mfma_f32_16x16x32_bf16 v[34:37], v[220:223], v[196:199], v[34:37]
	v_mfma_f32_16x16x32_bf16 v[26:29], v[228:231], v[196:199], v[26:29]
	v_mfma_f32_16x16x32_bf16 v[18:21], v[220:223], v[204:207], v[18:21]
	v_mfma_f32_16x16x32_bf16 v[10:13], v[228:231], v[204:207], v[10:13]
	v_mfma_f32_16x16x32_bf16 v[6:9], v[220:223], v[212:215], v[6:9]
	v_mfma_f32_16x16x32_bf16 v[2:5], v[228:231], v[212:215], v[2:5]
	s_add_u32 vcc_lo, vcc_lo, 0x100
	s_addc_u32 vcc_hi, vcc_hi, 0
	s_add_u32 s23, s23, 0x100
	s_addc_u32 s47, s47, 0
	s_cmp_ge_u32 s71, s68
	s_mov_b32 s2, s71
	s_barrier
	s_cbranch_scc0 .LBB0_318
	s_branch .Lafter_318
.LBB0_318:
	s_add_i32 s71, s2, 2
	s_add_u32 s98, vcc_lo, 0x80
	s_addc_u32 s3, vcc_hi, 0
	s_add_i32 s73, 0, 0x10000
	v_add_u32_e32 v0, s73, v143
	ds_read_b128 v[168:171], v0
	ds_read_b128 v[172:175], v0 offset:1024
	ds_read_b128 v[176:179], v0 offset:2048
	ds_read_b128 v[180:183], v0 offset:3072
	s_cmp_eq_u32 s22, s2
	s_cselect_b32 s2, s20, s98
	s_cselect_b32 s3, s21, s3
	s_cselect_b32 s99, s1, s47
	s_cselect_b32 s98, s0, s23
	s_add_i32 m0, s43, 0xc000
	ds_read_b128 v[184:187], v159
	ds_read_b128 v[188:191], v159 offset:1024
	ds_read_b128 v[192:195], v159 offset:2048
	ds_read_b128 v[196:199], v159 offset:3072
	ds_read_b128 v[200:203], v159 offset:4096
	ds_read_b128 v[204:207], v159 offset:5120
	ds_read_b128 v[208:211], v159 offset:6144
	ds_read_b128 v[212:215], v159 offset:7168
	global_load_lds_dwordx4 v152, vcc
	s_add_i32 m0, s43, 0xe000
	s_nop 0
	global_load_lds_dwordx4 v154, vcc
	s_waitcnt lgkmcnt(8)
	s_barrier
	s_waitcnt lgkmcnt(0)
	v_mfma_f32_16x16x32_bf16 v[126:129], v[168:171], v[184:187], v[126:129]
	v_mfma_f32_16x16x32_bf16 v[122:125], v[176:179], v[184:187], v[122:125]
	v_mfma_f32_16x16x32_bf16 v[118:121], v[168:171], v[192:195], v[118:121]
	v_mfma_f32_16x16x32_bf16 v[110:113], v[176:179], v[192:195], v[110:113]
	v_mfma_f32_16x16x32_bf16 v[102:105], v[168:171], v[200:203], v[102:105]
	v_mfma_f32_16x16x32_bf16 v[94:97], v[176:179], v[200:203], v[94:97]
	v_mfma_f32_16x16x32_bf16 v[86:89], v[168:171], v[208:211], v[86:89]
	v_mfma_f32_16x16x32_bf16 v[78:81], v[176:179], v[208:211], v[78:81]
	v_mfma_f32_16x16x32_bf16 v[126:129], v[172:175], v[188:191], v[126:129]
	v_mfma_f32_16x16x32_bf16 v[122:125], v[180:183], v[188:191], v[122:125]
	v_mfma_f32_16x16x32_bf16 v[118:121], v[172:175], v[196:199], v[118:121]
	v_mfma_f32_16x16x32_bf16 v[110:113], v[180:183], v[196:199], v[110:113]
	v_mfma_f32_16x16x32_bf16 v[102:105], v[172:175], v[204:207], v[102:105]
	v_mfma_f32_16x16x32_bf16 v[94:97], v[180:183], v[204:207], v[94:97]
	v_mfma_f32_16x16x32_bf16 v[86:89], v[172:175], v[212:215], v[86:89]
	v_mfma_f32_16x16x32_bf16 v[78:81], v[180:183], v[212:215], v[78:81]
	s_barrier
	s_add_i32 s70, 0, 0x14000
	s_add_i32 s73, s73, s41
	v_add_u32_e32 v0, s70, v143
	v_lshl_add_u64 v[130:131], s[98:99], 0, v[146:147]
	s_mov_b32 m0, s73
	ds_read_b128 v[216:219], v0
	ds_read_b128 v[220:223], v0 offset:1024
	ds_read_b128 v[224:227], v0 offset:2048
	ds_read_b128 v[228:231], v0 offset:3072
	global_load_lds_dwordx4 v146, s[98:99]
	v_lshl_add_u64 v[132:133], s[98:99], 0, v[150:151]
	s_add_i32 m0, s73, 0x2000
	s_nop 0
	global_load_lds_dwordx4 v150, s[98:99]
	s_barrier
	s_waitcnt lgkmcnt(0)
	v_mfma_f32_16x16x32_bf16 v[114:117], v[216:219], v[184:187], v[114:117]
	v_mfma_f32_16x16x32_bf16 v[106:109], v[224:227], v[184:187], v[106:109]
	v_mfma_f32_16x16x32_bf16 v[98:101], v[216:219], v[192:195], v[98:101]
	v_mfma_f32_16x16x32_bf16 v[90:93], v[224:227], v[192:195], v[90:93]
	v_mfma_f32_16x16x32_bf16 v[82:85], v[216:219], v[200:203], v[82:85]
	v_mfma_f32_16x16x32_bf16 v[74:77], v[224:227], v[200:203], v[74:77]
	v_mfma_f32_16x16x32_bf16 v[70:73], v[216:219], v[208:211], v[70:73]
	v_mfma_f32_16x16x32_bf16 v[66:69], v[224:227], v[208:211], v[66:69]
	v_mfma_f32_16x16x32_bf16 v[114:117], v[220:223], v[188:191], v[114:117]
	v_mfma_f32_16x16x32_bf16 v[106:109], v[228:231], v[188:191], v[106:109]
	v_mfma_f32_16x16x32_bf16 v[98:101], v[220:223], v[196:199], v[98:101]
	v_mfma_f32_16x16x32_bf16 v[90:93], v[228:231], v[196:199], v[90:93]
	v_mfma_f32_16x16x32_bf16 v[82:85], v[220:223], v[204:207], v[82:85]
	v_mfma_f32_16x16x32_bf16 v[74:77], v[228:231], v[204:207], v[74:77]
	v_mfma_f32_16x16x32_bf16 v[70:73], v[220:223], v[212:215], v[70:73]
	v_mfma_f32_16x16x32_bf16 v[66:69], v[228:231], v[212:215], v[66:69]
	s_mov_b32 m0, s43
	v_lshl_add_u64 v[156:157], s[2:3], 0, v[144:145]
	s_barrier
	ds_read_b128 v[184:187], v159 offset:16384
	ds_read_b128 v[188:191], v159 offset:17408
	ds_read_b128 v[192:195], v159 offset:18432
	ds_read_b128 v[196:199], v159 offset:19456
	ds_read_b128 v[200:203], v159 offset:20480
	ds_read_b128 v[204:207], v159 offset:21504
	ds_read_b128 v[208:211], v159 offset:22528
	ds_read_b128 v[212:215], v159 offset:23552
	global_load_lds_dwordx4 v144, s[2:3]
	v_lshl_add_u64 v[162:163], s[2:3], 0, v[148:149]
	s_mov_b32 m0, s44
	s_nop 0
	global_load_lds_dwordx4 v148, s[2:3]
	s_barrier
	s_waitcnt lgkmcnt(0)
	v_mfma_f32_16x16x32_bf16 v[62:65], v[168:171], v[184:187], v[62:65]
	v_mfma_f32_16x16x32_bf16 v[58:61], v[176:179], v[184:187], v[58:61]
	v_mfma_f32_16x16x32_bf16 v[54:57], v[168:171], v[192:195], v[54:57]
	v_mfma_f32_16x16x32_bf16 v[46:49], v[176:179], v[192:195], v[46:49]
	v_mfma_f32_16x16x32_bf16 v[38:41], v[168:171], v[200:203], v[38:41]
	v_mfma_f32_16x16x32_bf16 v[30:33], v[176:179], v[200:203], v[30:33]
	v_mfma_f32_16x16x32_bf16 v[22:25], v[168:171], v[208:211], v[22:25]
	v_mfma_f32_16x16x32_bf16 v[14:17], v[176:179], v[208:211], v[14:17]
	v_mfma_f32_16x16x32_bf16 v[62:65], v[172:175], v[188:191], v[62:65]
	v_mfma_f32_16x16x32_bf16 v[58:61], v[180:183], v[188:191], v[58:61]
	v_mfma_f32_16x16x32_bf16 v[54:57], v[172:175], v[196:199], v[54:57]
	v_mfma_f32_16x16x32_bf16 v[46:49], v[180:183], v[196:199], v[46:49]
	v_mfma_f32_16x16x32_bf16 v[38:41], v[172:175], v[204:207], v[38:41]
	v_mfma_f32_16x16x32_bf16 v[30:33], v[180:183], v[204:207], v[30:33]
	v_mfma_f32_16x16x32_bf16 v[22:25], v[172:175], v[212:215], v[22:25]
	v_mfma_f32_16x16x32_bf16 v[14:17], v[180:183], v[212:215], v[14:17]
	s_barrier
	s_add_u32 s98, s98, s96
	s_addc_u32 s99, s99, 0
	s_add_i32 s70, s70, s41
	s_mov_b32 m0, s70
	s_nop 0
	global_load_lds_dwordx4 v146, s[98:99]
	s_add_i32 m0, s70, 0x2000
	s_nop 0
	global_load_lds_dwordx4 v150, s[98:99]
	s_waitcnt vmcnt(6)
	s_barrier
	v_mfma_f32_16x16x32_bf16 v[50:53], v[216:219], v[184:187], v[50:53]
	v_mfma_f32_16x16x32_bf16 v[42:45], v[224:227], v[184:187], v[42:45]
	v_mfma_f32_16x16x32_bf16 v[34:37], v[216:219], v[192:195], v[34:37]
	v_mfma_f32_16x16x32_bf16 v[26:29], v[224:227], v[192:195], v[26:29]
	v_mfma_f32_16x16x32_bf16 v[18:21], v[216:219], v[200:203], v[18:21]
	v_mfma_f32_16x16x32_bf16 v[10:13], v[224:227], v[200:203], v[10:13]
	v_mfma_f32_16x16x32_bf16 v[6:9], v[216:219], v[208:211], v[6:9]
	v_mfma_f32_16x16x32_bf16 v[2:5], v[224:227], v[208:211], v[2:5]
	v_mfma_f32_16x16x32_bf16 v[50:53], v[220:223], v[188:191], v[50:53]
	v_mfma_f32_16x16x32_bf16 v[42:45], v[228:231], v[188:191], v[42:45]
	v_mfma_f32_16x16x32_bf16 v[34:37], v[220:223], v[196:199], v[34:37]
	v_mfma_f32_16x16x32_bf16 v[26:29], v[228:231], v[196:199], v[26:29]
	v_mfma_f32_16x16x32_bf16 v[18:21], v[220:223], v[204:207], v[18:21]
	v_mfma_f32_16x16x32_bf16 v[10:13], v[228:231], v[204:207], v[10:13]
	v_mfma_f32_16x16x32_bf16 v[6:9], v[220:223], v[212:215], v[6:9]
	v_mfma_f32_16x16x32_bf16 v[2:5], v[228:231], v[212:215], v[2:5]
	s_add_i32 s70, 0, 0x18000
	v_add_u32_e32 v0, s70, v143
	s_barrier
	ds_read_b128 v[168:171], v0
	ds_read_b128 v[172:175], v0 offset:1024
	ds_read_b128 v[176:179], v0 offset:2048
	ds_read_b128 v[180:183], v0 offset:3072
	s_add_u32 s2, s2, s96
	s_addc_u32 s3, s3, 0
	s_mov_b32 m0, s45
	ds_read_b128 v[184:187], v159 offset:32768
	ds_read_b128 v[188:191], v159 offset:33792
	ds_read_b128 v[192:195], v159 offset:34816
	ds_read_b128 v[196:199], v159 offset:35840
	ds_read_b128 v[200:203], v159 offset:36864
	ds_read_b128 v[204:207], v159 offset:37888
	ds_read_b128 v[208:211], v159 offset:38912
	ds_read_b128 v[212:215], v159 offset:39936
	global_load_lds_dwordx4 v144, s[2:3]
	s_mov_b32 m0, s40
	s_nop 0
	global_load_lds_dwordx4 v148, s[2:3]
	s_waitcnt lgkmcnt(8)
	s_barrier
	s_waitcnt lgkmcnt(0)
	v_mfma_f32_16x16x32_bf16 v[126:129], v[168:171], v[184:187], v[126:129]
	v_mfma_f32_16x16x32_bf16 v[122:125], v[176:179], v[184:187], v[122:125]
	v_mfma_f32_16x16x32_bf16 v[118:121], v[168:171], v[192:195], v[118:121]
	v_mfma_f32_16x16x32_bf16 v[110:113], v[176:179], v[192:195], v[110:113]
	v_mfma_f32_16x16x32_bf16 v[102:105], v[168:171], v[200:203], v[102:105]
	v_mfma_f32_16x16x32_bf16 v[94:97], v[176:179], v[200:203], v[94:97]
	v_mfma_f32_16x16x32_bf16 v[86:89], v[168:171], v[208:211], v[86:89]
	v_mfma_f32_16x16x32_bf16 v[78:81], v[176:179], v[208:211], v[78:81]
	v_mfma_f32_16x16x32_bf16 v[126:129], v[172:175], v[188:191], v[126:129]
	v_mfma_f32_16x16x32_bf16 v[122:125], v[180:183], v[188:191], v[122:125]
	v_mfma_f32_16x16x32_bf16 v[118:121], v[172:175], v[196:199], v[118:121]
	v_mfma_f32_16x16x32_bf16 v[110:113], v[180:183], v[196:199], v[110:113]
	v_mfma_f32_16x16x32_bf16 v[102:105], v[172:175], v[204:207], v[102:105]
	v_mfma_f32_16x16x32_bf16 v[94:97], v[180:183], v[204:207], v[94:97]
	v_mfma_f32_16x16x32_bf16 v[86:89], v[172:175], v[212:215], v[86:89]
	v_mfma_f32_16x16x32_bf16 v[78:81], v[180:183], v[212:215], v[78:81]
	s_barrier
	s_add_i32 s2, 0, 0x1c000
	s_add_i32 s3, s70, s41
	v_add_u32_e32 v0, s2, v143
	v_lshl_add_u64 v[130:131], v[130:131], 0, s[26:27]
	s_mov_b32 m0, s3
	ds_read_b128 v[216:219], v0
	ds_read_b128 v[220:223], v0 offset:1024
	ds_read_b128 v[224:227], v0 offset:2048
	ds_read_b128 v[228:231], v0 offset:3072
	global_load_lds_dwordx4 v[130:131], off
	v_lshl_add_u64 v[130:131], v[132:133], 0, s[26:27]
	s_add_i32 m0, s3, 0x2000
	s_nop 0
	global_load_lds_dwordx4 v[130:131], off
	s_barrier
	s_waitcnt lgkmcnt(0)
	v_mfma_f32_16x16x32_bf16 v[114:117], v[216:219], v[184:187], v[114:117]
	v_mfma_f32_16x16x32_bf16 v[106:109], v[224:227], v[184:187], v[106:109]
	v_mfma_f32_16x16x32_bf16 v[98:101], v[216:219], v[192:195], v[98:101]
	v_mfma_f32_16x16x32_bf16 v[90:93], v[224:227], v[192:195], v[90:93]
	v_mfma_f32_16x16x32_bf16 v[82:85], v[216:219], v[200:203], v[82:85]
	v_mfma_f32_16x16x32_bf16 v[74:77], v[224:227], v[200:203], v[74:77]
	v_mfma_f32_16x16x32_bf16 v[70:73], v[216:219], v[208:211], v[70:73]
	v_mfma_f32_16x16x32_bf16 v[66:69], v[224:227], v[208:211], v[66:69]
	v_mfma_f32_16x16x32_bf16 v[114:117], v[220:223], v[188:191], v[114:117]
	v_mfma_f32_16x16x32_bf16 v[106:109], v[228:231], v[188:191], v[106:109]
	v_mfma_f32_16x16x32_bf16 v[98:101], v[220:223], v[196:199], v[98:101]
	v_mfma_f32_16x16x32_bf16 v[90:93], v[228:231], v[196:199], v[90:93]
	v_mfma_f32_16x16x32_bf16 v[82:85], v[220:223], v[204:207], v[82:85]
	v_mfma_f32_16x16x32_bf16 v[74:77], v[228:231], v[204:207], v[74:77]
	v_mfma_f32_16x16x32_bf16 v[70:73], v[220:223], v[212:215], v[70:73]
	v_mfma_f32_16x16x32_bf16 v[66:69], v[228:231], v[212:215], v[66:69]
	s_mov_b32 m0, s66
	v_lshl_add_u64 v[130:131], v[156:157], 0, s[26:27]
	s_barrier
	ds_read_b128 v[184:187], v159 offset:49152
	ds_read_b128 v[188:191], v159 offset:50176
	ds_read_b128 v[192:195], v159 offset:51200
	ds_read_b128 v[196:199], v159 offset:52224
	ds_read_b128 v[200:203], v159 offset:53248
	ds_read_b128 v[204:207], v159 offset:54272
	ds_read_b128 v[208:211], v159 offset:55296
	ds_read_b128 v[212:215], v159 offset:56320
	global_load_lds_dwordx4 v[130:131], off
	v_lshl_add_u64 v[130:131], v[162:163], 0, s[26:27]
	s_mov_b32 m0, s67
	s_nop 0
	global_load_lds_dwordx4 v[130:131], off
	s_barrier
	s_waitcnt lgkmcnt(0)
	v_mfma_f32_16x16x32_bf16 v[62:65], v[168:171], v[184:187], v[62:65]
	v_mfma_f32_16x16x32_bf16 v[58:61], v[176:179], v[184:187], v[58:61]
	v_mfma_f32_16x16x32_bf16 v[54:57], v[168:171], v[192:195], v[54:57]
	v_mfma_f32_16x16x32_bf16 v[46:49], v[176:179], v[192:195], v[46:49]
	v_mfma_f32_16x16x32_bf16 v[38:41], v[168:171], v[200:203], v[38:41]
	v_mfma_f32_16x16x32_bf16 v[30:33], v[176:179], v[200:203], v[30:33]
	v_mfma_f32_16x16x32_bf16 v[22:25], v[168:171], v[208:211], v[22:25]
	v_mfma_f32_16x16x32_bf16 v[14:17], v[176:179], v[208:211], v[14:17]
	v_mfma_f32_16x16x32_bf16 v[62:65], v[172:175], v[188:191], v[62:65]
	v_mfma_f32_16x16x32_bf16 v[58:61], v[180:183], v[188:191], v[58:61]
	v_mfma_f32_16x16x32_bf16 v[54:57], v[172:175], v[196:199], v[54:57]
	v_mfma_f32_16x16x32_bf16 v[46:49], v[180:183], v[196:199], v[46:49]
	v_mfma_f32_16x16x32_bf16 v[38:41], v[172:175], v[204:207], v[38:41]
	v_mfma_f32_16x16x32_bf16 v[30:33], v[180:183], v[204:207], v[30:33]
	v_mfma_f32_16x16x32_bf16 v[22:25], v[172:175], v[212:215], v[22:25]
	v_mfma_f32_16x16x32_bf16 v[14:17], v[180:183], v[212:215], v[14:17]
	s_barrier
	s_add_i32 s2, s2, s41
	s_add_i32 m0, s2, 0xffffff80
	s_nop 0
	global_load_lds_dwordx4 v146, s[98:99] offset:128
	s_add_i32 m0, s2, 0x1f80
	s_nop 0
	global_load_lds_dwordx4 v150, s[98:99] offset:128
	s_waitcnt vmcnt(6)
	s_barrier
	v_mfma_f32_16x16x32_bf16 v[50:53], v[216:219], v[184:187], v[50:53]
	v_mfma_f32_16x16x32_bf16 v[42:45], v[224:227], v[184:187], v[42:45]
	v_mfma_f32_16x16x32_bf16 v[34:37], v[216:219], v[192:195], v[34:37]
	v_mfma_f32_16x16x32_bf16 v[26:29], v[224:227], v[192:195], v[26:29]
	v_mfma_f32_16x16x32_bf16 v[18:21], v[216:219], v[200:203], v[18:21]
	v_mfma_f32_16x16x32_bf16 v[10:13], v[224:227], v[200:203], v[10:13]
	v_mfma_f32_16x16x32_bf16 v[6:9], v[216:219], v[208:211], v[6:9]
	v_mfma_f32_16x16x32_bf16 v[2:5], v[224:227], v[208:211], v[2:5]
	v_mfma_f32_16x16x32_bf16 v[50:53], v[220:223], v[188:191], v[50:53]
	v_mfma_f32_16x16x32_bf16 v[42:45], v[228:231], v[188:191], v[42:45]
	v_mfma_f32_16x16x32_bf16 v[34:37], v[220:223], v[196:199], v[34:37]
	v_mfma_f32_16x16x32_bf16 v[26:29], v[228:231], v[196:199], v[26:29]
	v_mfma_f32_16x16x32_bf16 v[18:21], v[220:223], v[204:207], v[18:21]
	v_mfma_f32_16x16x32_bf16 v[10:13], v[228:231], v[204:207], v[10:13]
	v_mfma_f32_16x16x32_bf16 v[6:9], v[220:223], v[212:215], v[6:9]
	v_mfma_f32_16x16x32_bf16 v[2:5], v[228:231], v[212:215], v[2:5]
	s_add_u32 vcc_lo, vcc_lo, 0x100
	s_addc_u32 vcc_hi, vcc_hi, 0
	s_add_u32 s23, s23, 0x100
	s_addc_u32 s47, s47, 0
	s_cmp_ge_u32 s71, s68
	s_mov_b32 s2, s71
	s_barrier
	s_cbranch_scc0 .LBB0_318

.LBB0_436:
	s_ashr_i32 s37, s36, 31
	v_cmp_lt_i64_e32 vcc, s[28:29], v[138:139]
	s_lshl_b64 s[22:23], s[36:37], 19
	v_readlane_b32 s28, v253, 45
	v_readlane_b32 s29, v253, 46
	s_add_u32 s30, s28, s22
	s_addc_u32 s31, s29, s23
	s_and_b64 s[22:23], vcc, exec
	s_cselect_b32 s22, s31, s21
	s_cselect_b32 s23, s30, s20
	s_ashr_i32 s43, s42, 31
	s_lshl_b64 s[28:29], s[42:43], 19
	v_readlane_b32 s46, v253, 31
	v_readlane_b32 s47, v253, 32
	s_add_u32 s46, s46, s28
	s_addc_u32 s47, s47, s29
	s_and_b64 s[28:29], vcc, exec
	s_cselect_b32 s37, s47, s3
	s_cselect_b32 s43, s46, s2
	s_add_u32 s20, s20, 0x40080
	s_addc_u32 s21, s21, 0
	s_add_u32 s65, s2, 0x100
	s_addc_u32 s66, s3, 0
	s_mov_b32 s67, -2
	s_waitcnt lgkmcnt(0)
	s_add_u32 s2, s20, 0xfffc0080
	s_addc_u32 s3, s21, -1
	s_add_i32 s68, 0, 0x10000
	v_add_u32_e32 v130, s68, v143
	ds_read_b128 v[168:171], v130
	ds_read_b128 v[172:175], v130 offset:1024
	ds_read_b128 v[176:179], v130 offset:2048
	ds_read_b128 v[180:183], v130 offset:3072
	s_cmp_eq_u32 s67, 12
	s_cselect_b32 s29, s22, s3
	s_cselect_b32 s28, s23, s2
	s_cselect_b32 s3, s37, s66
	s_cselect_b32 s2, s43, s65
	s_add_i32 m0, s99, 0xc000
	ds_read_b128 v[184:187], v157
	ds_read_b128 v[188:191], v157 offset:1024
	ds_read_b128 v[192:195], v157 offset:2048
	ds_read_b128 v[196:199], v157 offset:3072
	ds_read_b128 v[200:203], v157 offset:4096
	ds_read_b128 v[204:207], v157 offset:5120
	ds_read_b128 v[208:211], v157 offset:6144
	ds_read_b128 v[212:215], v157 offset:7168
	global_load_lds_dwordx4 v150, s[20:21]
	v_lshl_add_u64 v[130:131], s[20:21], 0, v[152:153]
	s_add_i32 m0, s99, 0xe000
	s_nop 0
	global_load_lds_dwordx4 v152, s[20:21]
	s_waitcnt lgkmcnt(8)
	s_barrier
	s_waitcnt lgkmcnt(0)
	v_mfma_f32_16x16x32_bf16 v[126:129], v[168:171], v[184:187], 0
	v_mfma_f32_16x16x32_bf16 v[114:117], v[176:179], v[184:187], 0
	v_mfma_f32_16x16x32_bf16 v[110:113], v[168:171], v[192:195], 0
	v_mfma_f32_16x16x32_bf16 v[98:101], v[176:179], v[192:195], 0
	v_mfma_f32_16x16x32_bf16 v[94:97], v[168:171], v[200:203], 0
	v_mfma_f32_16x16x32_bf16 v[82:85], v[176:179], v[200:203], 0
	v_mfma_f32_16x16x32_bf16 v[78:81], v[168:171], v[208:211], 0
	v_mfma_f32_16x16x32_bf16 v[66:69], v[176:179], v[208:211], 0
	v_mfma_f32_16x16x32_bf16 v[126:129], v[172:175], v[188:191], v[126:129]
	v_mfma_f32_16x16x32_bf16 v[114:117], v[180:183], v[188:191], v[114:117]
	v_mfma_f32_16x16x32_bf16 v[110:113], v[172:175], v[196:199], v[110:113]
	v_mfma_f32_16x16x32_bf16 v[98:101], v[180:183], v[196:199], v[98:101]
	v_mfma_f32_16x16x32_bf16 v[94:97], v[172:175], v[204:207], v[94:97]
	v_mfma_f32_16x16x32_bf16 v[82:85], v[180:183], v[204:207], v[82:85]
	v_mfma_f32_16x16x32_bf16 v[78:81], v[172:175], v[212:215], v[78:81]
	v_mfma_f32_16x16x32_bf16 v[66:69], v[180:183], v[212:215], v[66:69]
	s_barrier
	s_add_i32 s70, 0, 0x14000
	v_add_u32_e32 v130, s70, v143
	s_add_i32 s68, s68, s98
	ds_read_b128 v[216:219], v130
	ds_read_b128 v[220:223], v130 offset:1024
	ds_read_b128 v[224:227], v130 offset:2048
	ds_read_b128 v[228:231], v130 offset:3072
	s_mov_b32 m0, s68
	s_nop 0
	global_load_lds_dwordx4 v0, s[2:3]
	s_add_i32 m0, s68, 0x2000
	s_nop 0
	global_load_lds_dwordx4 v144, s[2:3]
	s_barrier
	s_waitcnt lgkmcnt(0)
	v_mfma_f32_16x16x32_bf16 v[122:125], v[216:219], v[184:187], 0
	v_mfma_f32_16x16x32_bf16 v[118:121], v[224:227], v[184:187], 0
	v_mfma_f32_16x16x32_bf16 v[106:109], v[216:219], v[192:195], 0
	v_mfma_f32_16x16x32_bf16 v[102:105], v[224:227], v[192:195], 0
	v_mfma_f32_16x16x32_bf16 v[90:93], v[216:219], v[200:203], 0
	v_mfma_f32_16x16x32_bf16 v[86:89], v[224:227], v[200:203], 0
	v_mfma_f32_16x16x32_bf16 v[74:77], v[216:219], v[208:211], 0
	v_mfma_f32_16x16x32_bf16 v[70:73], v[224:227], v[208:211], 0
	v_mfma_f32_16x16x32_bf16 v[122:125], v[220:223], v[188:191], v[122:125]
	v_mfma_f32_16x16x32_bf16 v[118:121], v[228:231], v[188:191], v[118:121]
	v_mfma_f32_16x16x32_bf16 v[106:109], v[220:223], v[196:199], v[106:109]
	v_mfma_f32_16x16x32_bf16 v[102:105], v[228:231], v[196:199], v[102:105]
	v_mfma_f32_16x16x32_bf16 v[90:93], v[220:223], v[204:207], v[90:93]
	v_mfma_f32_16x16x32_bf16 v[86:89], v[228:231], v[204:207], v[86:89]
	v_mfma_f32_16x16x32_bf16 v[74:77], v[220:223], v[212:215], v[74:77]
	v_mfma_f32_16x16x32_bf16 v[70:73], v[228:231], v[212:215], v[70:73]
	s_mov_b32 m0, s99
	v_lshl_add_u64 v[154:155], s[28:29], 0, v[148:149]
	s_barrier
	ds_read_b128 v[184:187], v157 offset:16384
	ds_read_b128 v[188:191], v157 offset:17408
	ds_read_b128 v[192:195], v157 offset:18432
	ds_read_b128 v[196:199], v157 offset:19456
	ds_read_b128 v[200:203], v157 offset:20480
	ds_read_b128 v[204:207], v157 offset:21504
	ds_read_b128 v[208:211], v157 offset:22528
	ds_read_b128 v[212:215], v157 offset:23552
	global_load_lds_dwordx4 v148, s[28:29]
	v_lshl_add_u64 v[158:159], s[28:29], 0, v[146:147]
	s_mov_b32 m0, s41
	s_nop 0
	global_load_lds_dwordx4 v146, s[28:29]
	s_barrier
	s_waitcnt lgkmcnt(0)
	v_mfma_f32_16x16x32_bf16 v[62:65], v[168:171], v[184:187], 0
	v_mfma_f32_16x16x32_bf16 v[50:53], v[176:179], v[184:187], 0
	v_mfma_f32_16x16x32_bf16 v[46:49], v[168:171], v[192:195], 0
	v_mfma_f32_16x16x32_bf16 v[34:37], v[176:179], v[192:195], 0
	v_mfma_f32_16x16x32_bf16 v[30:33], v[168:171], v[200:203], 0
	v_mfma_f32_16x16x32_bf16 v[18:21], v[176:179], v[200:203], 0
	v_mfma_f32_16x16x32_bf16 v[14:17], v[168:171], v[208:211], 0
	v_mfma_f32_16x16x32_bf16 v[6:9], v[176:179], v[208:211], 0
	v_mfma_f32_16x16x32_bf16 v[62:65], v[172:175], v[188:191], v[62:65]
	v_mfma_f32_16x16x32_bf16 v[50:53], v[180:183], v[188:191], v[50:53]
	v_mfma_f32_16x16x32_bf16 v[46:49], v[172:175], v[196:199], v[46:49]
	v_mfma_f32_16x16x32_bf16 v[34:37], v[180:183], v[196:199], v[34:37]
	v_mfma_f32_16x16x32_bf16 v[30:33], v[172:175], v[204:207], v[30:33]
	v_mfma_f32_16x16x32_bf16 v[18:21], v[180:183], v[204:207], v[18:21]
	v_mfma_f32_16x16x32_bf16 v[14:17], v[172:175], v[212:215], v[14:17]
	v_mfma_f32_16x16x32_bf16 v[6:9], v[180:183], v[212:215], v[6:9]
	s_barrier
	s_add_u32 s68, s2, 0x40000
	s_addc_u32 s69, s3, 0
	s_add_i32 s70, s70, s98
	s_mov_b32 m0, s70
	s_nop 0
	global_load_lds_dwordx4 v0, s[68:69]
	v_lshl_add_u64 v[162:163], s[68:69], 0, v[144:145]
	s_add_i32 m0, s70, 0x2000
	s_nop 0
	global_load_lds_dwordx4 v144, s[68:69]
	s_waitcnt vmcnt(6)
	s_barrier
	v_mfma_f32_16x16x32_bf16 v[58:61], v[216:219], v[184:187], 0
	v_mfma_f32_16x16x32_bf16 v[54:57], v[224:227], v[184:187], 0
	v_mfma_f32_16x16x32_bf16 v[42:45], v[216:219], v[192:195], 0
	v_mfma_f32_16x16x32_bf16 v[38:41], v[224:227], v[192:195], 0
	v_mfma_f32_16x16x32_bf16 v[26:29], v[216:219], v[200:203], 0
	v_mfma_f32_16x16x32_bf16 v[22:25], v[224:227], v[200:203], 0
	v_mfma_f32_16x16x32_bf16 v[10:13], v[216:219], v[208:211], 0
	v_mfma_f32_16x16x32_bf16 v[2:5], v[224:227], v[208:211], 0
	v_mfma_f32_16x16x32_bf16 v[58:61], v[220:223], v[188:191], v[58:61]
	v_mfma_f32_16x16x32_bf16 v[54:57], v[228:231], v[188:191], v[54:57]
	v_mfma_f32_16x16x32_bf16 v[42:45], v[220:223], v[196:199], v[42:45]
	v_mfma_f32_16x16x32_bf16 v[38:41], v[228:231], v[196:199], v[38:41]
	v_mfma_f32_16x16x32_bf16 v[26:29], v[220:223], v[204:207], v[26:29]
	v_mfma_f32_16x16x32_bf16 v[22:25], v[228:231], v[204:207], v[22:25]
	v_mfma_f32_16x16x32_bf16 v[10:13], v[220:223], v[212:215], v[10:13]
	v_mfma_f32_16x16x32_bf16 v[2:5], v[228:231], v[212:215], v[2:5]
	s_add_i32 s68, 0, 0x18000
	v_add_u32_e32 v162, s68, v143
	s_barrier
	ds_read_b128 v[168:171], v162
	ds_read_b128 v[172:175], v162 offset:1024
	ds_read_b128 v[176:179], v162 offset:2048
	ds_read_b128 v[180:183], v162 offset:3072
	s_add_u32 s28, s28, 0x40000
	s_addc_u32 s29, s29, 0
	s_mov_b32 m0, s96
	ds_read_b128 v[184:187], v157 offset:32768
	ds_read_b128 v[188:191], v157 offset:33792
	ds_read_b128 v[192:195], v157 offset:34816
	ds_read_b128 v[196:199], v157 offset:35840
	ds_read_b128 v[200:203], v157 offset:36864
	ds_read_b128 v[204:207], v157 offset:37888
	ds_read_b128 v[208:211], v157 offset:38912
	ds_read_b128 v[212:215], v157 offset:39936
	global_load_lds_dwordx4 v148, s[28:29]
	v_lshl_add_u64 v[162:163], s[28:29], 0, v[146:147]
	s_mov_b32 m0, s35
	s_nop 0
	global_load_lds_dwordx4 v146, s[28:29]
	s_waitcnt lgkmcnt(8)
	s_barrier
	s_waitcnt lgkmcnt(0)
	v_mfma_f32_16x16x32_bf16 v[126:129], v[168:171], v[184:187], v[126:129]
	v_mfma_f32_16x16x32_bf16 v[114:117], v[176:179], v[184:187], v[114:117]
	v_mfma_f32_16x16x32_bf16 v[110:113], v[168:171], v[192:195], v[110:113]
	v_mfma_f32_16x16x32_bf16 v[98:101], v[176:179], v[192:195], v[98:101]
	v_mfma_f32_16x16x32_bf16 v[94:97], v[168:171], v[200:203], v[94:97]
	v_mfma_f32_16x16x32_bf16 v[82:85], v[176:179], v[200:203], v[82:85]
	v_mfma_f32_16x16x32_bf16 v[78:81], v[168:171], v[208:211], v[78:81]
	v_mfma_f32_16x16x32_bf16 v[66:69], v[176:179], v[208:211], v[66:69]
	v_mfma_f32_16x16x32_bf16 v[126:129], v[172:175], v[188:191], v[126:129]
	v_mfma_f32_16x16x32_bf16 v[114:117], v[180:183], v[188:191], v[114:117]
	v_mfma_f32_16x16x32_bf16 v[110:113], v[172:175], v[196:199], v[110:113]
	v_mfma_f32_16x16x32_bf16 v[98:101], v[180:183], v[196:199], v[98:101]
	v_mfma_f32_16x16x32_bf16 v[94:97], v[172:175], v[204:207], v[94:97]
	v_mfma_f32_16x16x32_bf16 v[82:85], v[180:183], v[204:207], v[82:85]
	v_mfma_f32_16x16x32_bf16 v[78:81], v[172:175], v[212:215], v[78:81]
	v_mfma_f32_16x16x32_bf16 v[66:69], v[180:183], v[212:215], v[66:69]
	s_barrier
	s_add_i32 s28, 0, 0x1c000
	s_add_i32 s29, s68, s98
	v_add_u32_e32 v162, s28, v143
	s_add_i32 m0, s29, 0xffffff80
	ds_read_b128 v[216:219], v162
	ds_read_b128 v[220:223], v162 offset:1024
	ds_read_b128 v[224:227], v162 offset:2048
	ds_read_b128 v[228:231], v162 offset:3072
	global_load_lds_dwordx4 v0, s[2:3] offset:128
	s_add_i32 m0, s29, 0x1f80
	s_nop 0
	global_load_lds_dwordx4 v144, s[2:3] offset:128
	s_barrier
	s_waitcnt lgkmcnt(0)
	v_mfma_f32_16x16x32_bf16 v[122:125], v[216:219], v[184:187], v[122:125]
	v_mfma_f32_16x16x32_bf16 v[118:121], v[224:227], v[184:187], v[118:121]
	v_mfma_f32_16x16x32_bf16 v[106:109], v[216:219], v[192:195], v[106:109]
	v_mfma_f32_16x16x32_bf16 v[102:105], v[224:227], v[192:195], v[102:105]
	v_mfma_f32_16x16x32_bf16 v[90:93], v[216:219], v[200:203], v[90:93]
	v_mfma_f32_16x16x32_bf16 v[86:89], v[224:227], v[200:203], v[86:89]
	v_mfma_f32_16x16x32_bf16 v[74:77], v[216:219], v[208:211], v[74:77]
	v_mfma_f32_16x16x32_bf16 v[70:73], v[224:227], v[208:211], v[70:73]
	v_mfma_f32_16x16x32_bf16 v[122:125], v[220:223], v[188:191], v[122:125]
	v_mfma_f32_16x16x32_bf16 v[118:121], v[228:231], v[188:191], v[118:121]
	v_mfma_f32_16x16x32_bf16 v[106:109], v[220:223], v[196:199], v[106:109]
	v_mfma_f32_16x16x32_bf16 v[102:105], v[228:231], v[196:199], v[102:105]
	v_mfma_f32_16x16x32_bf16 v[90:93], v[220:223], v[204:207], v[90:93]
	v_mfma_f32_16x16x32_bf16 v[86:89], v[228:231], v[204:207], v[86:89]
	v_mfma_f32_16x16x32_bf16 v[74:77], v[220:223], v[212:215], v[74:77]
	v_mfma_f32_16x16x32_bf16 v[70:73], v[228:231], v[212:215], v[70:73]
	s_mov_b32 m0, s33
	v_lshl_add_u64 v[130:131], v[154:155], 0, s[26:27]
	s_barrier
	ds_read_b128 v[184:187], v157 offset:49152
	ds_read_b128 v[188:191], v157 offset:50176
	ds_read_b128 v[192:195], v157 offset:51200
	ds_read_b128 v[196:199], v157 offset:52224
	ds_read_b128 v[200:203], v157 offset:53248
	ds_read_b128 v[204:207], v157 offset:54272
	ds_read_b128 v[208:211], v157 offset:55296
	ds_read_b128 v[212:215], v157 offset:56320
	global_load_lds_dwordx4 v[130:131], off
	v_lshl_add_u64 v[130:131], v[158:159], 0, s[26:27]
	s_mov_b32 m0, s44
	s_nop 0
	global_load_lds_dwordx4 v[130:131], off
	s_barrier
	s_waitcnt lgkmcnt(0)
	v_mfma_f32_16x16x32_bf16 v[62:65], v[168:171], v[184:187], v[62:65]
	v_mfma_f32_16x16x32_bf16 v[50:53], v[176:179], v[184:187], v[50:53]
	v_mfma_f32_16x16x32_bf16 v[46:49], v[168:171], v[192:195], v[46:49]
	v_mfma_f32_16x16x32_bf16 v[34:37], v[176:179], v[192:195], v[34:37]
	v_mfma_f32_16x16x32_bf16 v[30:33], v[168:171], v[200:203], v[30:33]
	v_mfma_f32_16x16x32_bf16 v[18:21], v[176:179], v[200:203], v[18:21]
	v_mfma_f32_16x16x32_bf16 v[14:17], v[168:171], v[208:211], v[14:17]
	v_mfma_f32_16x16x32_bf16 v[6:9], v[176:179], v[208:211], v[6:9]
	v_mfma_f32_16x16x32_bf16 v[62:65], v[172:175], v[188:191], v[62:65]
	v_mfma_f32_16x16x32_bf16 v[50:53], v[180:183], v[188:191], v[50:53]
	v_mfma_f32_16x16x32_bf16 v[46:49], v[172:175], v[196:199], v[46:49]
	v_mfma_f32_16x16x32_bf16 v[34:37], v[180:183], v[196:199], v[34:37]
	v_mfma_f32_16x16x32_bf16 v[30:33], v[172:175], v[204:207], v[30:33]
	v_mfma_f32_16x16x32_bf16 v[18:21], v[180:183], v[204:207], v[18:21]
	v_mfma_f32_16x16x32_bf16 v[14:17], v[172:175], v[212:215], v[14:17]
	v_mfma_f32_16x16x32_bf16 v[6:9], v[180:183], v[212:215], v[6:9]
	s_barrier
	s_add_u32 s2, s2, 0x40080
	s_addc_u32 s3, s3, 0
	s_add_i32 s28, s28, s98
	s_mov_b32 m0, s28
	s_nop 0
	global_load_lds_dwordx4 v0, s[2:3]
	v_lshl_add_u64 v[130:131], s[2:3], 0, v[144:145]
	s_add_i32 m0, s28, 0x2000
	s_nop 0
	global_load_lds_dwordx4 v144, s[2:3]
	s_waitcnt vmcnt(6)
	s_barrier
	v_mfma_f32_16x16x32_bf16 v[58:61], v[216:219], v[184:187], v[58:61]
	v_mfma_f32_16x16x32_bf16 v[54:57], v[224:227], v[184:187], v[54:57]
	v_mfma_f32_16x16x32_bf16 v[42:45], v[216:219], v[192:195], v[42:45]
	v_mfma_f32_16x16x32_bf16 v[38:41], v[224:227], v[192:195], v[38:41]
	v_mfma_f32_16x16x32_bf16 v[26:29], v[216:219], v[200:203], v[26:29]
	v_mfma_f32_16x16x32_bf16 v[22:25], v[224:227], v[200:203], v[22:25]
	v_mfma_f32_16x16x32_bf16 v[10:13], v[216:219], v[208:211], v[10:13]
	v_mfma_f32_16x16x32_bf16 v[2:5], v[224:227], v[208:211], v[2:5]
	v_mfma_f32_16x16x32_bf16 v[58:61], v[220:223], v[188:191], v[58:61]
	v_mfma_f32_16x16x32_bf16 v[54:57], v[228:231], v[188:191], v[54:57]
	v_mfma_f32_16x16x32_bf16 v[42:45], v[220:223], v[196:199], v[42:45]
	v_mfma_f32_16x16x32_bf16 v[38:41], v[228:231], v[196:199], v[38:41]
	v_mfma_f32_16x16x32_bf16 v[26:29], v[220:223], v[204:207], v[26:29]
	v_mfma_f32_16x16x32_bf16 v[22:25], v[228:231], v[204:207], v[22:25]
	v_mfma_f32_16x16x32_bf16 v[10:13], v[220:223], v[212:215], v[10:13]
	v_mfma_f32_16x16x32_bf16 v[2:5], v[228:231], v[212:215], v[2:5]
	s_add_i32 s67, s67, 2
	s_add_u32 s20, s20, 0x100
	s_addc_u32 s21, s21, 0
	s_add_u32 s65, s65, 0x100
	s_addc_u32 s66, s66, 0
	s_cmp_gt_u32 s67, 13
	s_barrier
	s_cbranch_scc0 .LBB0_437
	s_branch .Lafter_437
.LBB0_437:
	s_add_u32 s2, s20, 0xfffc0080
	s_addc_u32 s3, s21, -1
	s_add_i32 s68, 0, 0x10000
	v_add_u32_e32 v130, s68, v143
	ds_read_b128 v[168:171], v130
	ds_read_b128 v[172:175], v130 offset:1024
	ds_read_b128 v[176:179], v130 offset:2048
	ds_read_b128 v[180:183], v130 offset:3072
	s_cmp_eq_u32 s67, 12
	s_cselect_b32 s29, s22, s3
	s_cselect_b32 s28, s23, s2
	s_cselect_b32 s3, s37, s66
	s_cselect_b32 s2, s43, s65
	s_add_i32 m0, s99, 0xc000
	ds_read_b128 v[184:187], v157
	ds_read_b128 v[188:191], v157 offset:1024
	ds_read_b128 v[192:195], v157 offset:2048
	ds_read_b128 v[196:199], v157 offset:3072
	ds_read_b128 v[200:203], v157 offset:4096
	ds_read_b128 v[204:207], v157 offset:5120
	ds_read_b128 v[208:211], v157 offset:6144
	ds_read_b128 v[212:215], v157 offset:7168
	global_load_lds_dwordx4 v150, s[20:21]
	v_lshl_add_u64 v[130:131], s[20:21], 0, v[152:153]
	s_add_i32 m0, s99, 0xe000
	s_nop 0
	global_load_lds_dwordx4 v152, s[20:21]
	s_waitcnt lgkmcnt(8)
	s_barrier
	s_waitcnt lgkmcnt(0)
	v_mfma_f32_16x16x32_bf16 v[126:129], v[168:171], v[184:187], v[126:129]
	v_mfma_f32_16x16x32_bf16 v[114:117], v[176:179], v[184:187], v[114:117]
	v_mfma_f32_16x16x32_bf16 v[110:113], v[168:171], v[192:195], v[110:113]
	v_mfma_f32_16x16x32_bf16 v[98:101], v[176:179], v[192:195], v[98:101]
	v_mfma_f32_16x16x32_bf16 v[94:97], v[168:171], v[200:203], v[94:97]
	v_mfma_f32_16x16x32_bf16 v[82:85], v[176:179], v[200:203], v[82:85]
	v_mfma_f32_16x16x32_bf16 v[78:81], v[168:171], v[208:211], v[78:81]
	v_mfma_f32_16x16x32_bf16 v[66:69], v[176:179], v[208:211], v[66:69]
	v_mfma_f32_16x16x32_bf16 v[126:129], v[172:175], v[188:191], v[126:129]
	v_mfma_f32_16x16x32_bf16 v[114:117], v[180:183], v[188:191], v[114:117]
	v_mfma_f32_16x16x32_bf16 v[110:113], v[172:175], v[196:199], v[110:113]
	v_mfma_f32_16x16x32_bf16 v[98:101], v[180:183], v[196:199], v[98:101]
	v_mfma_f32_16x16x32_bf16 v[94:97], v[172:175], v[204:207], v[94:97]
	v_mfma_f32_16x16x32_bf16 v[82:85], v[180:183], v[204:207], v[82:85]
	v_mfma_f32_16x16x32_bf16 v[78:81], v[172:175], v[212:215], v[78:81]
	v_mfma_f32_16x16x32_bf16 v[66:69], v[180:183], v[212:215], v[66:69]
	s_barrier
	s_add_i32 s70, 0, 0x14000
	v_add_u32_e32 v130, s70, v143
	s_add_i32 s68, s68, s98
	ds_read_b128 v[216:219], v130
	ds_read_b128 v[220:223], v130 offset:1024
	ds_read_b128 v[224:227], v130 offset:2048
	ds_read_b128 v[228:231], v130 offset:3072
	s_mov_b32 m0, s68
	s_nop 0
	global_load_lds_dwordx4 v0, s[2:3]
	s_add_i32 m0, s68, 0x2000
	s_nop 0
	global_load_lds_dwordx4 v144, s[2:3]
	s_barrier
	s_waitcnt lgkmcnt(0)
	v_mfma_f32_16x16x32_bf16 v[122:125], v[216:219], v[184:187], v[122:125]
	v_mfma_f32_16x16x32_bf16 v[118:121], v[224:227], v[184:187], v[118:121]
	v_mfma_f32_16x16x32_bf16 v[106:109], v[216:219], v[192:195], v[106:109]
	v_mfma_f32_16x16x32_bf16 v[102:105], v[224:227], v[192:195], v[102:105]
	v_mfma_f32_16x16x32_bf16 v[90:93], v[216:219], v[200:203], v[90:93]
	v_mfma_f32_16x16x32_bf16 v[86:89], v[224:227], v[200:203], v[86:89]
	v_mfma_f32_16x16x32_bf16 v[74:77], v[216:219], v[208:211], v[74:77]
	v_mfma_f32_16x16x32_bf16 v[70:73], v[224:227], v[208:211], v[70:73]
	v_mfma_f32_16x16x32_bf16 v[122:125], v[220:223], v[188:191], v[122:125]
	v_mfma_f32_16x16x32_bf16 v[118:121], v[228:231], v[188:191], v[118:121]
	v_mfma_f32_16x16x32_bf16 v[106:109], v[220:223], v[196:199], v[106:109]
	v_mfma_f32_16x16x32_bf16 v[102:105], v[228:231], v[196:199], v[102:105]
	v_mfma_f32_16x16x32_bf16 v[90:93], v[220:223], v[204:207], v[90:93]
	v_mfma_f32_16x16x32_bf16 v[86:89], v[228:231], v[204:207], v[86:89]
	v_mfma_f32_16x16x32_bf16 v[74:77], v[220:223], v[212:215], v[74:77]
	v_mfma_f32_16x16x32_bf16 v[70:73], v[228:231], v[212:215], v[70:73]
	s_mov_b32 m0, s99
	v_lshl_add_u64 v[154:155], s[28:29], 0, v[148:149]
	s_barrier
	ds_read_b128 v[184:187], v157 offset:16384
	ds_read_b128 v[188:191], v157 offset:17408
	ds_read_b128 v[192:195], v157 offset:18432
	ds_read_b128 v[196:199], v157 offset:19456
	ds_read_b128 v[200:203], v157 offset:20480
	ds_read_b128 v[204:207], v157 offset:21504
	ds_read_b128 v[208:211], v157 offset:22528
	ds_read_b128 v[212:215], v157 offset:23552
	global_load_lds_dwordx4 v148, s[28:29]
	v_lshl_add_u64 v[158:159], s[28:29], 0, v[146:147]
	s_mov_b32 m0, s41
	s_nop 0
	global_load_lds_dwordx4 v146, s[28:29]
	s_barrier
	s_waitcnt lgkmcnt(0)
	v_mfma_f32_16x16x32_bf16 v[62:65], v[168:171], v[184:187], v[62:65]
	v_mfma_f32_16x16x32_bf16 v[50:53], v[176:179], v[184:187], v[50:53]
	v_mfma_f32_16x16x32_bf16 v[46:49], v[168:171], v[192:195], v[46:49]
	v_mfma_f32_16x16x32_bf16 v[34:37], v[176:179], v[192:195], v[34:37]
	v_mfma_f32_16x16x32_bf16 v[30:33], v[168:171], v[200:203], v[30:33]
	v_mfma_f32_16x16x32_bf16 v[18:21], v[176:179], v[200:203], v[18:21]
	v_mfma_f32_16x16x32_bf16 v[14:17], v[168:171], v[208:211], v[14:17]
	v_mfma_f32_16x16x32_bf16 v[6:9], v[176:179], v[208:211], v[6:9]
	v_mfma_f32_16x16x32_bf16 v[62:65], v[172:175], v[188:191], v[62:65]
	v_mfma_f32_16x16x32_bf16 v[50:53], v[180:183], v[188:191], v[50:53]
	v_mfma_f32_16x16x32_bf16 v[46:49], v[172:175], v[196:199], v[46:49]
	v_mfma_f32_16x16x32_bf16 v[34:37], v[180:183], v[196:199], v[34:37]
	v_mfma_f32_16x16x32_bf16 v[30:33], v[172:175], v[204:207], v[30:33]
	v_mfma_f32_16x16x32_bf16 v[18:21], v[180:183], v[204:207], v[18:21]
	v_mfma_f32_16x16x32_bf16 v[14:17], v[172:175], v[212:215], v[14:17]
	v_mfma_f32_16x16x32_bf16 v[6:9], v[180:183], v[212:215], v[6:9]
	s_barrier
	s_add_u32 s68, s2, 0x40000
	s_addc_u32 s69, s3, 0
	s_add_i32 s70, s70, s98
	s_mov_b32 m0, s70
	s_nop 0
	global_load_lds_dwordx4 v0, s[68:69]
	v_lshl_add_u64 v[162:163], s[68:69], 0, v[144:145]
	s_add_i32 m0, s70, 0x2000
	s_nop 0
	global_load_lds_dwordx4 v144, s[68:69]
	s_waitcnt vmcnt(6)
	s_barrier
	v_mfma_f32_16x16x32_bf16 v[58:61], v[216:219], v[184:187], v[58:61]
	v_mfma_f32_16x16x32_bf16 v[54:57], v[224:227], v[184:187], v[54:57]
	v_mfma_f32_16x16x32_bf16 v[42:45], v[216:219], v[192:195], v[42:45]
	v_mfma_f32_16x16x32_bf16 v[38:41], v[224:227], v[192:195], v[38:41]
	v_mfma_f32_16x16x32_bf16 v[26:29], v[216:219], v[200:203], v[26:29]
	v_mfma_f32_16x16x32_bf16 v[22:25], v[224:227], v[200:203], v[22:25]
	v_mfma_f32_16x16x32_bf16 v[10:13], v[216:219], v[208:211], v[10:13]
	v_mfma_f32_16x16x32_bf16 v[2:5], v[224:227], v[208:211], v[2:5]
	v_mfma_f32_16x16x32_bf16 v[58:61], v[220:223], v[188:191], v[58:61]
	v_mfma_f32_16x16x32_bf16 v[54:57], v[228:231], v[188:191], v[54:57]
	v_mfma_f32_16x16x32_bf16 v[42:45], v[220:223], v[196:199], v[42:45]
	v_mfma_f32_16x16x32_bf16 v[38:41], v[228:231], v[196:199], v[38:41]
	v_mfma_f32_16x16x32_bf16 v[26:29], v[220:223], v[204:207], v[26:29]
	v_mfma_f32_16x16x32_bf16 v[22:25], v[228:231], v[204:207], v[22:25]
	v_mfma_f32_16x16x32_bf16 v[10:13], v[220:223], v[212:215], v[10:13]
	v_mfma_f32_16x16x32_bf16 v[2:5], v[228:231], v[212:215], v[2:5]
	s_add_i32 s68, 0, 0x18000
	v_add_u32_e32 v162, s68, v143
	s_barrier
	ds_read_b128 v[168:171], v162
	ds_read_b128 v[172:175], v162 offset:1024
	ds_read_b128 v[176:179], v162 offset:2048
	ds_read_b128 v[180:183], v162 offset:3072
	s_add_u32 s28, s28, 0x40000
	s_addc_u32 s29, s29, 0
	s_mov_b32 m0, s96
	ds_read_b128 v[184:187], v157 offset:32768
	ds_read_b128 v[188:191], v157 offset:33792
	ds_read_b128 v[192:195], v157 offset:34816
	ds_read_b128 v[196:199], v157 offset:35840
	ds_read_b128 v[200:203], v157 offset:36864
	ds_read_b128 v[204:207], v157 offset:37888
	ds_read_b128 v[208:211], v157 offset:38912
	ds_read_b128 v[212:215], v157 offset:39936
	global_load_lds_dwordx4 v148, s[28:29]
	v_lshl_add_u64 v[162:163], s[28:29], 0, v[146:147]
	s_mov_b32 m0, s35
	s_nop 0
	global_load_lds_dwordx4 v146, s[28:29]
	s_waitcnt lgkmcnt(8)
	s_barrier
	s_waitcnt lgkmcnt(0)
	v_mfma_f32_16x16x32_bf16 v[126:129], v[168:171], v[184:187], v[126:129]
	v_mfma_f32_16x16x32_bf16 v[114:117], v[176:179], v[184:187], v[114:117]
	v_mfma_f32_16x16x32_bf16 v[110:113], v[168:171], v[192:195], v[110:113]
	v_mfma_f32_16x16x32_bf16 v[98:101], v[176:179], v[192:195], v[98:101]
	v_mfma_f32_16x16x32_bf16 v[94:97], v[168:171], v[200:203], v[94:97]
	v_mfma_f32_16x16x32_bf16 v[82:85], v[176:179], v[200:203], v[82:85]
	v_mfma_f32_16x16x32_bf16 v[78:81], v[168:171], v[208:211], v[78:81]
	v_mfma_f32_16x16x32_bf16 v[66:69], v[176:179], v[208:211], v[66:69]
	v_mfma_f32_16x16x32_bf16 v[126:129], v[172:175], v[188:191], v[126:129]
	v_mfma_f32_16x16x32_bf16 v[114:117], v[180:183], v[188:191], v[114:117]
	v_mfma_f32_16x16x32_bf16 v[110:113], v[172:175], v[196:199], v[110:113]
	v_mfma_f32_16x16x32_bf16 v[98:101], v[180:183], v[196:199], v[98:101]
	v_mfma_f32_16x16x32_bf16 v[94:97], v[172:175], v[204:207], v[94:97]
	v_mfma_f32_16x16x32_bf16 v[82:85], v[180:183], v[204:207], v[82:85]
	v_mfma_f32_16x16x32_bf16 v[78:81], v[172:175], v[212:215], v[78:81]
	v_mfma_f32_16x16x32_bf16 v[66:69], v[180:183], v[212:215], v[66:69]
	s_barrier
	s_add_i32 s28, 0, 0x1c000
	s_add_i32 s29, s68, s98
	v_add_u32_e32 v162, s28, v143
	s_add_i32 m0, s29, 0xffffff80
	ds_read_b128 v[216:219], v162
	ds_read_b128 v[220:223], v162 offset:1024
	ds_read_b128 v[224:227], v162 offset:2048
	ds_read_b128 v[228:231], v162 offset:3072
	global_load_lds_dwordx4 v0, s[2:3] offset:128
	s_add_i32 m0, s29, 0x1f80
	s_nop 0
	global_load_lds_dwordx4 v144, s[2:3] offset:128
	s_barrier
	s_waitcnt lgkmcnt(0)
	v_mfma_f32_16x16x32_bf16 v[122:125], v[216:219], v[184:187], v[122:125]
	v_mfma_f32_16x16x32_bf16 v[118:121], v[224:227], v[184:187], v[118:121]
	v_mfma_f32_16x16x32_bf16 v[106:109], v[216:219], v[192:195], v[106:109]
	v_mfma_f32_16x16x32_bf16 v[102:105], v[224:227], v[192:195], v[102:105]
	v_mfma_f32_16x16x32_bf16 v[90:93], v[216:219], v[200:203], v[90:93]
	v_mfma_f32_16x16x32_bf16 v[86:89], v[224:227], v[200:203], v[86:89]
	v_mfma_f32_16x16x32_bf16 v[74:77], v[216:219], v[208:211], v[74:77]
	v_mfma_f32_16x16x32_bf16 v[70:73], v[224:227], v[208:211], v[70:73]
	v_mfma_f32_16x16x32_bf16 v[122:125], v[220:223], v[188:191], v[122:125]
	v_mfma_f32_16x16x32_bf16 v[118:121], v[228:231], v[188:191], v[118:121]
	v_mfma_f32_16x16x32_bf16 v[106:109], v[220:223], v[196:199], v[106:109]
	v_mfma_f32_16x16x32_bf16 v[102:105], v[228:231], v[196:199], v[102:105]
	v_mfma_f32_16x16x32_bf16 v[90:93], v[220:223], v[204:207], v[90:93]
	v_mfma_f32_16x16x32_bf16 v[86:89], v[228:231], v[204:207], v[86:89]
	v_mfma_f32_16x16x32_bf16 v[74:77], v[220:223], v[212:215], v[74:77]
	v_mfma_f32_16x16x32_bf16 v[70:73], v[228:231], v[212:215], v[70:73]
	s_mov_b32 m0, s33
	v_lshl_add_u64 v[130:131], v[154:155], 0, s[26:27]
	s_barrier
	ds_read_b128 v[184:187], v157 offset:49152
	ds_read_b128 v[188:191], v157 offset:50176
	ds_read_b128 v[192:195], v157 offset:51200
	ds_read_b128 v[196:199], v157 offset:52224
	ds_read_b128 v[200:203], v157 offset:53248
	ds_read_b128 v[204:207], v157 offset:54272
	ds_read_b128 v[208:211], v157 offset:55296
	ds_read_b128 v[212:215], v157 offset:56320
	global_load_lds_dwordx4 v[130:131], off
	v_lshl_add_u64 v[130:131], v[158:159], 0, s[26:27]
	s_mov_b32 m0, s44
	s_nop 0
	global_load_lds_dwordx4 v[130:131], off
	s_barrier
	s_waitcnt lgkmcnt(0)
	v_mfma_f32_16x16x32_bf16 v[62:65], v[168:171], v[184:187], v[62:65]
	v_mfma_f32_16x16x32_bf16 v[50:53], v[176:179], v[184:187], v[50:53]
	v_mfma_f32_16x16x32_bf16 v[46:49], v[168:171], v[192:195], v[46:49]
	v_mfma_f32_16x16x32_bf16 v[34:37], v[176:179], v[192:195], v[34:37]
	v_mfma_f32_16x16x32_bf16 v[30:33], v[168:171], v[200:203], v[30:33]
	v_mfma_f32_16x16x32_bf16 v[18:21], v[176:179], v[200:203], v[18:21]
	v_mfma_f32_16x16x32_bf16 v[14:17], v[168:171], v[208:211], v[14:17]
	v_mfma_f32_16x16x32_bf16 v[6:9], v[176:179], v[208:211], v[6:9]
	v_mfma_f32_16x16x32_bf16 v[62:65], v[172:175], v[188:191], v[62:65]
	v_mfma_f32_16x16x32_bf16 v[50:53], v[180:183], v[188:191], v[50:53]
	v_mfma_f32_16x16x32_bf16 v[46:49], v[172:175], v[196:199], v[46:49]
	v_mfma_f32_16x16x32_bf16 v[34:37], v[180:183], v[196:199], v[34:37]
	v_mfma_f32_16x16x32_bf16 v[30:33], v[172:175], v[204:207], v[30:33]
	v_mfma_f32_16x16x32_bf16 v[18:21], v[180:183], v[204:207], v[18:21]
	v_mfma_f32_16x16x32_bf16 v[14:17], v[172:175], v[212:215], v[14:17]
	v_mfma_f32_16x16x32_bf16 v[6:9], v[180:183], v[212:215], v[6:9]
	s_barrier
	s_add_u32 s2, s2, 0x40080
	s_addc_u32 s3, s3, 0
	s_add_i32 s28, s28, s98
	s_mov_b32 m0, s28
	s_nop 0
	global_load_lds_dwordx4 v0, s[2:3]
	v_lshl_add_u64 v[130:131], s[2:3], 0, v[144:145]
	s_add_i32 m0, s28, 0x2000
	s_nop 0
	global_load_lds_dwordx4 v144, s[2:3]
	s_waitcnt vmcnt(6)
	s_barrier
	v_mfma_f32_16x16x32_bf16 v[58:61], v[216:219], v[184:187], v[58:61]
	v_mfma_f32_16x16x32_bf16 v[54:57], v[224:227], v[184:187], v[54:57]
	v_mfma_f32_16x16x32_bf16 v[42:45], v[216:219], v[192:195], v[42:45]
	v_mfma_f32_16x16x32_bf16 v[38:41], v[224:227], v[192:195], v[38:41]
	v_mfma_f32_16x16x32_bf16 v[26:29], v[216:219], v[200:203], v[26:29]
	v_mfma_f32_16x16x32_bf16 v[22:25], v[224:227], v[200:203], v[22:25]
	v_mfma_f32_16x16x32_bf16 v[10:13], v[216:219], v[208:211], v[10:13]
	v_mfma_f32_16x16x32_bf16 v[2:5], v[224:227], v[208:211], v[2:5]
	v_mfma_f32_16x16x32_bf16 v[58:61], v[220:223], v[188:191], v[58:61]
	v_mfma_f32_16x16x32_bf16 v[54:57], v[228:231], v[188:191], v[54:57]
	v_mfma_f32_16x16x32_bf16 v[42:45], v[220:223], v[196:199], v[42:45]
	v_mfma_f32_16x16x32_bf16 v[38:41], v[228:231], v[196:199], v[38:41]
	v_mfma_f32_16x16x32_bf16 v[26:29], v[220:223], v[204:207], v[26:29]
	v_mfma_f32_16x16x32_bf16 v[22:25], v[228:231], v[204:207], v[22:25]
	v_mfma_f32_16x16x32_bf16 v[10:13], v[220:223], v[212:215], v[10:13]
	v_mfma_f32_16x16x32_bf16 v[2:5], v[228:231], v[212:215], v[2:5]
	s_add_i32 s67, s67, 2
	s_add_u32 s20, s20, 0x100
	s_addc_u32 s21, s21, 0
	s_add_u32 s65, s65, 0x100
	s_addc_u32 s66, s66, 0
	s_cmp_gt_u32 s67, 13
	s_barrier
	s_cbranch_scc0 .LBB0_437
